# X1B prompt rows stored in lane-linear 16x32 block layout (P6 EpiOut stores contiguous; P7 A-operand LDS-DMA + ds_read and P8 fused-norm epilogue loads adapted)
# speedup vs baseline: 1.0305x; 1.0147x over previous
; __device__ __forceinline__ u32x4 pack8(const f32x4 a, const f32x4 b) { u32x4 w; w.x = cvt_pk_bf16(a[0], a[1]); w.y = cvt_pk_bf16(a[2], a[3]); w.z = cvt_pk_bf16(b[0], b[1]); w.w = cvt_pk_bf16(b[2], b[3]); return w; }
;     __device__ __forceinline__ void operator()(AccRef acc, const Unit& u, int wr, int wc, int fr, int fq) const {
;         const float* xb = (u.pm < 128) ? xp : xs - (size_t)NPROMPT * D;
; #pragma unroll
;         for (int ai = 0; ai < 2; ++ai)
; #pragma unroll
;             for (int m = 0; m < 4; ++m) { const int row = u.pm * 256 + ai * 128 + wr * 64 + m * 16 + fr; float sq = 0.f;
; #pragma unroll
;                 for (int bj = 0; bj < 2; ++bj) { const size_t off = (size_t)row * D + u.pn * 256 + bj * 128 + wc * 32 + 8 * fq;
;                     const f32x4 a0 = *(const f32x4*)(xb + off) + acc[ai][bj][m][0], a1 = *(const f32x4*)(xb + off + 4) + acc[ai][bj][m][1];
;                     *(u32x4*)(X1B + off) = pack8(a0, a1);
;                     sq += (a0[0] * a0[0] + a0[1] * a0[1]) + (a0[2] * a0[2] + a0[3] * a0[3]) + (a1[0] * a1[0] + a1[1] * a1[1]) + (a1[2] * a1[2] + a1[3] * a1[3]); }
;                 sq += __shfl_xor(sq, 16); sq += __shfl_xor(sq, 32);
;                 if (fq == 0) atomicAdd(ssq + row, sq); }
.LBB0_727:
	s_cmpk_lt_i32 s38, 0x80
	s_cselect_b32 s63, s37, s70
	s_cselect_b32 s62, s36, s47
	s_movk_i32 s100, 0x100
	s_cselect_b32 s100, 0x1000, s100
	s_cselect_b64 s[98:99], -1, 0
	s_mov_b32 s101, 0
	v_lshl_add_u32 v148, s38, 8, v158
	s_lshl_b32 s2, s60, 8
	s_ashr_i32 s34, s2, 31
	v_ashrrev_i32_e32 v149, 31, v148
	v_mov_b32_e32 v147, s34
	v_or_b32_e32 v146, s2, v144
	v_lshlrev_b64 v[170:171], 11, v[148:149]
	v_lshl_add_u64 v[170:171], v[170:171], 0, v[146:147]
	v_lshl_add_u64 v[162:163], v[170:171], 2, s[62:63]
	v_lshlrev_b64 v[164:165], 12, v[148:149]
	v_lshl_add_u64 v[164:165], v[164:165], 0, s[14:15]
	v_lshrrev_b32_e32 v172, 5, v146
	v_lshlrev_b32_e32 v172, 10, v172
	v_and_b32_e32 v173, 63, v136
	v_lshl_add_u32 v172, v173, 4, v172
	v_and_b32_e32 v173, 15, v136
	v_lshlrev_b32_e32 v173, 12, v173
	v_sub_u32_e32 v172, v172, v173
	v_lshlrev_b32_e32 v173, 1, v146
	v_cndmask_b32_e64 v172, v173, v172, s[98:99]
	v_ashrrev_i32_e32 v173, 31, v172
	v_lshl_add_u64 v[164:165], v[164:165], 0, v[172:173]
	v_lshl_add_u64 v[176:177], v[164:165], 0, s[100:101]
	v_lshl_add_u64 v[166:167], v[148:149], 2, s[30:31]
	v_xor_b32_e32 v168, 16, v157
	v_xor_b32_e32 v169, 32, v157
	v_lshlrev_b32_e32 v168, 2, v168
	v_lshlrev_b32_e32 v169, 2, v169
	global_load_dwordx4 v[178:181], v[162:163], off
	global_load_dwordx4 v[182:185], v[162:163], off offset:16
	global_load_dwordx4 v[186:189], v[162:163], off offset:512
	global_load_dwordx4 v[190:193], v[162:163], off offset:528
	s_mov_b64 s[98:99], 0x20000
	v_lshl_add_u64 v[162:163], v[162:163], 0, s[98:99]
	global_load_dwordx4 v[194:197], v[162:163], off
	global_load_dwordx4 v[198:201], v[162:163], off offset:16
	global_load_dwordx4 v[202:205], v[162:163], off offset:512
	global_load_dwordx4 v[206:209], v[162:163], off offset:528
	s_mov_b64 s[98:99], 0x20000
	v_lshl_add_u64 v[162:163], v[162:163], 0, s[98:99]
	global_load_dwordx4 v[210:213], v[162:163], off
	global_load_dwordx4 v[214:217], v[162:163], off offset:16
	global_load_dwordx4 v[218:221], v[162:163], off offset:512
	global_load_dwordx4 v[222:225], v[162:163], off offset:528
	s_mov_b64 s[98:99], 0x20000
	v_lshl_add_u64 v[162:163], v[162:163], 0, s[98:99]
	global_load_dwordx4 v[226:229], v[162:163], off
	global_load_dwordx4 v[230:233], v[162:163], off offset:16
	global_load_dwordx4 v[234:237], v[162:163], off offset:512
	global_load_dwordx4 v[238:241], v[162:163], off offset:528
	s_mov_b64 s[98:99], 0xa0000
	v_lshl_add_u64 v[162:163], v[162:163], 0, s[98:99]
	s_waitcnt vmcnt(12)
	v_pk_add_f32 v[124:125], v[124:125], v[178:179]
	v_pk_add_f32 v[126:127], v[126:127], v[180:181]
	v_pk_add_f32 v[120:121], v[120:121], v[182:183]
	v_pk_add_f32 v[122:123], v[122:123], v[184:185]
	v_cvt_pk_bf16_f32 v172, v124, v125
	v_cvt_pk_bf16_f32 v173, v126, v127
	v_cvt_pk_bf16_f32 v174, v120, v121
	v_cvt_pk_bf16_f32 v175, v122, v123
	global_store_dwordx4 v[164:165], v[172:175], off
	v_mul_f32_e32 v125, v125, v125
	v_fmac_f32_e32 v125, v124, v124
	v_mul_f32_e32 v127, v127, v127
	v_fmac_f32_e32 v127, v126, v126
	v_mul_f32_e32 v121, v121, v121
	v_fmac_f32_e32 v121, v120, v120
	v_mul_f32_e32 v123, v123, v123
	v_fmac_f32_e32 v123, v122, v122
	v_add_f32_e32 v124, v125, v127
	v_add_f32_e32 v124, v124, v121
	v_add_f32_e32 v124, v123, v124
	v_pk_add_f32 v[116:117], v[116:117], v[186:187]
	v_pk_add_f32 v[118:119], v[118:119], v[188:189]
	v_pk_add_f32 v[112:113], v[112:113], v[190:191]
	v_pk_add_f32 v[114:115], v[114:115], v[192:193]
	v_cvt_pk_bf16_f32 v172, v116, v117
	v_cvt_pk_bf16_f32 v173, v118, v119
	v_cvt_pk_bf16_f32 v174, v112, v113
	v_cvt_pk_bf16_f32 v175, v114, v115
	global_store_dwordx4 v[176:177], v[172:175], off
	v_mul_f32_e32 v117, v117, v117
	v_fmac_f32_e32 v117, v116, v116
	v_mul_f32_e32 v119, v119, v119
	v_fmac_f32_e32 v119, v118, v118
	v_mul_f32_e32 v113, v113, v113
	v_fmac_f32_e32 v113, v112, v112
	v_mul_f32_e32 v115, v115, v115
	v_fmac_f32_e32 v115, v114, v114
	v_add_f32_e32 v116, v117, v119
	v_add_f32_e32 v116, v116, v113
	v_add_f32_e32 v116, v115, v116
	v_add_f32_e32 v170, v124, v116
	ds_bpermute_b32 v171, v168, v170
	s_waitcnt lgkmcnt(0)
	v_add_f32_e32 v170, v170, v171
	ds_bpermute_b32 v171, v169, v170
	s_mov_b64 s[98:99], 0x10000
	v_lshl_add_u64 v[164:165], v[164:165], 0, s[98:99]
	v_lshl_add_u64 v[176:177], v[176:177], 0, s[98:99]
	s_and_saveexec_b64 s[34:35], s[0:1]
	s_waitcnt lgkmcnt(0)
	v_add_f32_e32 v170, v170, v171
	global_atomic_add_f32 v[166:167], v170, off
	s_or_b64 exec, exec, s[34:35]
	global_load_dwordx4 v[178:181], v[162:163], off
	global_load_dwordx4 v[182:185], v[162:163], off offset:16
	global_load_dwordx4 v[186:189], v[162:163], off offset:512
	global_load_dwordx4 v[190:193], v[162:163], off offset:528
	s_mov_b64 s[98:99], 0x20000
	v_lshl_add_u64 v[162:163], v[162:163], 0, s[98:99]
	s_waitcnt vmcnt(15)
	v_pk_add_f32 v[108:109], v[108:109], v[194:195]
	v_pk_add_f32 v[110:111], v[110:111], v[196:197]
	v_pk_add_f32 v[104:105], v[104:105], v[198:199]
	v_pk_add_f32 v[106:107], v[106:107], v[200:201]
	v_cvt_pk_bf16_f32 v172, v108, v109
	v_cvt_pk_bf16_f32 v173, v110, v111
	v_cvt_pk_bf16_f32 v174, v104, v105
	v_cvt_pk_bf16_f32 v175, v106, v107
	global_store_dwordx4 v[164:165], v[172:175], off
	v_mul_f32_e32 v109, v109, v109
	v_fmac_f32_e32 v109, v108, v108
	v_mul_f32_e32 v111, v111, v111
	v_fmac_f32_e32 v111, v110, v110
	v_mul_f32_e32 v105, v105, v105
	v_fmac_f32_e32 v105, v104, v104
	v_mul_f32_e32 v107, v107, v107
	v_fmac_f32_e32 v107, v106, v106
	v_add_f32_e32 v108, v109, v111
	v_add_f32_e32 v108, v108, v105
	v_add_f32_e32 v108, v107, v108
	v_pk_add_f32 v[100:101], v[100:101], v[202:203]
	v_pk_add_f32 v[102:103], v[102:103], v[204:205]
	v_pk_add_f32 v[96:97], v[96:97], v[206:207]
	v_pk_add_f32 v[98:99], v[98:99], v[208:209]
	v_cvt_pk_bf16_f32 v172, v100, v101
	v_cvt_pk_bf16_f32 v173, v102, v103
	v_cvt_pk_bf16_f32 v174, v96, v97
	v_cvt_pk_bf16_f32 v175, v98, v99
	global_store_dwordx4 v[176:177], v[172:175], off
	v_mul_f32_e32 v101, v101, v101
	v_fmac_f32_e32 v101, v100, v100
	v_mul_f32_e32 v103, v103, v103
	v_fmac_f32_e32 v103, v102, v102
	v_mul_f32_e32 v97, v97, v97
	v_fmac_f32_e32 v97, v96, v96
	v_mul_f32_e32 v99, v99, v99
	v_fmac_f32_e32 v99, v98, v98
	v_add_f32_e32 v100, v101, v103
	v_add_f32_e32 v100, v100, v97
	v_add_f32_e32 v100, v99, v100
	v_add_f32_e32 v170, v108, v100
	ds_bpermute_b32 v171, v168, v170
	s_waitcnt lgkmcnt(0)
; __device__ __forceinline__ u32x4 pack8(const f32x4 a, const f32x4 b) { u32x4 w; w.x = cvt_pk_bf16(a[0], a[1]); w.y = cvt_pk_bf16(a[2], a[3]); w.z = cvt_pk_bf16(b[0], b[1]); w.w = cvt_pk_bf16(b[2], b[3]); return w; }
;     __device__ __forceinline__ void operator()(AccRef acc, const Unit& u, int wr, int wc, int fr, int fq) const {
;         const float* xb = (u.pm < 128) ? xp : xs - (size_t)NPROMPT * D;
; #pragma unroll
;         for (int ai = 0; ai < 2; ++ai)
; #pragma unroll
;             for (int m = 0; m < 4; ++m) { const int row = u.pm * 256 + ai * 128 + wr * 64 + m * 16 + fr; float sq = 0.f;
; #pragma unroll
;                 for (int bj = 0; bj < 2; ++bj) { const size_t off = (size_t)row * D + u.pn * 256 + bj * 128 + wc * 32 + 8 * fq;
;                     const f32x4 a0 = *(const f32x4*)(xb + off) + acc[ai][bj][m][0], a1 = *(const f32x4*)(xb + off + 4) + acc[ai][bj][m][1];
;                     *(u32x4*)(X1B + off) = pack8(a0, a1);
;                     sq += (a0[0] * a0[0] + a0[1] * a0[1]) + (a0[2] * a0[2] + a0[3] * a0[3]) + (a1[0] * a1[0] + a1[1] * a1[1]) + (a1[2] * a1[2] + a1[3] * a1[3]); }
;                 sq += __shfl_xor(sq, 16); sq += __shfl_xor(sq, 32);
;                 if (fq == 0) atomicAdd(ssq + row, sq); }
	v_add_f32_e32 v170, v170, v171
	ds_bpermute_b32 v171, v169, v170
	s_mov_b64 s[98:99], 0x10000
	v_lshl_add_u64 v[164:165], v[164:165], 0, s[98:99]
	v_lshl_add_u64 v[176:177], v[176:177], 0, s[98:99]
	s_and_saveexec_b64 s[34:35], s[0:1]
	s_waitcnt lgkmcnt(0)
	v_add_f32_e32 v170, v170, v171
	global_atomic_add_f32 v[166:167], v170, off offset:64
	s_or_b64 exec, exec, s[34:35]
	global_load_dwordx4 v[194:197], v[162:163], off
	global_load_dwordx4 v[198:201], v[162:163], off offset:16
	global_load_dwordx4 v[202:205], v[162:163], off offset:512
	global_load_dwordx4 v[206:209], v[162:163], off offset:528
	s_mov_b64 s[98:99], 0x20000
	v_lshl_add_u64 v[162:163], v[162:163], 0, s[98:99]
	s_waitcnt vmcnt(18)
	v_pk_add_f32 v[92:93], v[92:93], v[210:211]
	v_pk_add_f32 v[94:95], v[94:95], v[212:213]
	v_pk_add_f32 v[88:89], v[88:89], v[214:215]
	v_pk_add_f32 v[90:91], v[90:91], v[216:217]
	v_cvt_pk_bf16_f32 v172, v92, v93
	v_cvt_pk_bf16_f32 v173, v94, v95
	v_cvt_pk_bf16_f32 v174, v88, v89
	v_cvt_pk_bf16_f32 v175, v90, v91
	global_store_dwordx4 v[164:165], v[172:175], off
	v_mul_f32_e32 v93, v93, v93
	v_fmac_f32_e32 v93, v92, v92
	v_mul_f32_e32 v95, v95, v95
	v_fmac_f32_e32 v95, v94, v94
	v_mul_f32_e32 v89, v89, v89
	v_fmac_f32_e32 v89, v88, v88
	v_mul_f32_e32 v91, v91, v91
	v_fmac_f32_e32 v91, v90, v90
	v_add_f32_e32 v92, v93, v95
	v_add_f32_e32 v92, v92, v89
	v_add_f32_e32 v92, v91, v92
	v_pk_add_f32 v[84:85], v[84:85], v[218:219]
	v_pk_add_f32 v[86:87], v[86:87], v[220:221]
	v_pk_add_f32 v[80:81], v[80:81], v[222:223]
	v_pk_add_f32 v[82:83], v[82:83], v[224:225]
	v_cvt_pk_bf16_f32 v172, v84, v85
	v_cvt_pk_bf16_f32 v173, v86, v87
	v_cvt_pk_bf16_f32 v174, v80, v81
	v_cvt_pk_bf16_f32 v175, v82, v83
	global_store_dwordx4 v[176:177], v[172:175], off
	v_mul_f32_e32 v85, v85, v85
	v_fmac_f32_e32 v85, v84, v84
	v_mul_f32_e32 v87, v87, v87
	v_fmac_f32_e32 v87, v86, v86
	v_mul_f32_e32 v81, v81, v81
	v_fmac_f32_e32 v81, v80, v80
	v_mul_f32_e32 v83, v83, v83
	v_fmac_f32_e32 v83, v82, v82
	v_add_f32_e32 v84, v85, v87
	v_add_f32_e32 v84, v84, v81
	v_add_f32_e32 v84, v83, v84
	v_add_f32_e32 v170, v92, v84
	ds_bpermute_b32 v171, v168, v170
	s_waitcnt lgkmcnt(0)
	v_add_f32_e32 v170, v170, v171
	ds_bpermute_b32 v171, v169, v170
	s_mov_b64 s[98:99], 0x10000
	v_lshl_add_u64 v[164:165], v[164:165], 0, s[98:99]
	v_lshl_add_u64 v[176:177], v[176:177], 0, s[98:99]
	s_and_saveexec_b64 s[34:35], s[0:1]
	s_waitcnt lgkmcnt(0)
	v_add_f32_e32 v170, v170, v171
	global_atomic_add_f32 v[166:167], v170, off offset:128
	s_or_b64 exec, exec, s[34:35]
	global_load_dwordx4 v[210:213], v[162:163], off
	global_load_dwordx4 v[214:217], v[162:163], off offset:16
	global_load_dwordx4 v[218:221], v[162:163], off offset:512
	global_load_dwordx4 v[222:225], v[162:163], off offset:528
	s_mov_b64 s[98:99], 0x20000
	v_lshl_add_u64 v[162:163], v[162:163], 0, s[98:99]
	s_waitcnt vmcnt(21)
	v_pk_add_f32 v[76:77], v[76:77], v[226:227]
	v_pk_add_f32 v[78:79], v[78:79], v[228:229]
	v_pk_add_f32 v[72:73], v[72:73], v[230:231]
	v_pk_add_f32 v[74:75], v[74:75], v[232:233]
	v_cvt_pk_bf16_f32 v172, v76, v77
	v_cvt_pk_bf16_f32 v173, v78, v79
	v_cvt_pk_bf16_f32 v174, v72, v73
	v_cvt_pk_bf16_f32 v175, v74, v75
	global_store_dwordx4 v[164:165], v[172:175], off
	v_mul_f32_e32 v77, v77, v77
	v_fmac_f32_e32 v77, v76, v76
	v_mul_f32_e32 v79, v79, v79
	v_fmac_f32_e32 v79, v78, v78
	v_mul_f32_e32 v73, v73, v73
	v_fmac_f32_e32 v73, v72, v72
	v_mul_f32_e32 v75, v75, v75
	v_fmac_f32_e32 v75, v74, v74
	v_add_f32_e32 v76, v77, v79
	v_add_f32_e32 v76, v76, v73
	v_add_f32_e32 v76, v75, v76
	v_pk_add_f32 v[68:69], v[68:69], v[234:235]
	v_pk_add_f32 v[70:71], v[70:71], v[236:237]
	v_pk_add_f32 v[64:65], v[64:65], v[238:239]
	v_pk_add_f32 v[66:67], v[66:67], v[240:241]
	v_cvt_pk_bf16_f32 v172, v68, v69
	v_cvt_pk_bf16_f32 v173, v70, v71
	v_cvt_pk_bf16_f32 v174, v64, v65
	v_cvt_pk_bf16_f32 v175, v66, v67
	global_store_dwordx4 v[176:177], v[172:175], off
	v_mul_f32_e32 v69, v69, v69
	v_fmac_f32_e32 v69, v68, v68
	v_mul_f32_e32 v71, v71, v71
	v_fmac_f32_e32 v71, v70, v70
	v_mul_f32_e32 v65, v65, v65
	v_fmac_f32_e32 v65, v64, v64
	v_mul_f32_e32 v67, v67, v67
	v_fmac_f32_e32 v67, v66, v66
	v_add_f32_e32 v68, v69, v71
	v_add_f32_e32 v68, v68, v65
	v_add_f32_e32 v68, v67, v68
	v_add_f32_e32 v170, v76, v68
	ds_bpermute_b32 v171, v168, v170
	s_waitcnt lgkmcnt(0)
	v_add_f32_e32 v170, v170, v171
	ds_bpermute_b32 v171, v169, v170
	s_mov_b64 s[98:99], 0x50000
	v_lshl_add_u64 v[164:165], v[164:165], 0, s[98:99]
	v_lshl_add_u64 v[176:177], v[176:177], 0, s[98:99]
	s_and_saveexec_b64 s[34:35], s[0:1]
	s_waitcnt lgkmcnt(0)
	v_add_f32_e32 v170, v170, v171
	global_atomic_add_f32 v[166:167], v170, off offset:192
	s_or_b64 exec, exec, s[34:35]
	global_load_dwordx4 v[226:229], v[162:163], off
	global_load_dwordx4 v[230:233], v[162:163], off offset:16
	global_load_dwordx4 v[234:237], v[162:163], off offset:512
	global_load_dwordx4 v[238:241], v[162:163], off offset:528
	s_waitcnt vmcnt(21)
; __device__ __forceinline__ u32x4 pack8(const f32x4 a, const f32x4 b) { u32x4 w; w.x = cvt_pk_bf16(a[0], a[1]); w.y = cvt_pk_bf16(a[2], a[3]); w.z = cvt_pk_bf16(b[0], b[1]); w.w = cvt_pk_bf16(b[2], b[3]); return w; }
;     __device__ __forceinline__ void operator()(AccRef acc, const Unit& u, int wr, int wc, int fr, int fq) const {
;         const float* xb = (u.pm < 128) ? xp : xs - (size_t)NPROMPT * D;
; #pragma unroll
;         for (int ai = 0; ai < 2; ++ai)
; #pragma unroll
;             for (int m = 0; m < 4; ++m) { const int row = u.pm * 256 + ai * 128 + wr * 64 + m * 16 + fr; float sq = 0.f;
; #pragma unroll
;                 for (int bj = 0; bj < 2; ++bj) { const size_t off = (size_t)row * D + u.pn * 256 + bj * 128 + wc * 32 + 8 * fq;
;                     const f32x4 a0 = *(const f32x4*)(xb + off) + acc[ai][bj][m][0], a1 = *(const f32x4*)(xb + off + 4) + acc[ai][bj][m][1];
;                     *(u32x4*)(X1B + off) = pack8(a0, a1);
;                     sq += (a0[0] * a0[0] + a0[1] * a0[1]) + (a0[2] * a0[2] + a0[3] * a0[3]) + (a1[0] * a1[0] + a1[1] * a1[1]) + (a1[2] * a1[2] + a1[3] * a1[3]); }
;                 sq += __shfl_xor(sq, 16); sq += __shfl_xor(sq, 32);
;                 if (fq == 0) atomicAdd(ssq + row, sq); }
	v_pk_add_f32 v[60:61], v[60:61], v[178:179]
	v_pk_add_f32 v[62:63], v[62:63], v[180:181]
	v_pk_add_f32 v[56:57], v[56:57], v[182:183]
	v_pk_add_f32 v[58:59], v[58:59], v[184:185]
	v_cvt_pk_bf16_f32 v172, v60, v61
	v_cvt_pk_bf16_f32 v173, v62, v63
	v_cvt_pk_bf16_f32 v174, v56, v57
	v_cvt_pk_bf16_f32 v175, v58, v59
	global_store_dwordx4 v[164:165], v[172:175], off
	v_mul_f32_e32 v61, v61, v61
	v_fmac_f32_e32 v61, v60, v60
	v_mul_f32_e32 v63, v63, v63
	v_fmac_f32_e32 v63, v62, v62
	v_mul_f32_e32 v57, v57, v57
	v_fmac_f32_e32 v57, v56, v56
	v_mul_f32_e32 v59, v59, v59
	v_fmac_f32_e32 v59, v58, v58
	v_add_f32_e32 v60, v61, v63
	v_add_f32_e32 v60, v60, v57
	v_add_f32_e32 v60, v59, v60
	v_pk_add_f32 v[52:53], v[52:53], v[186:187]
	v_pk_add_f32 v[54:55], v[54:55], v[188:189]
	v_pk_add_f32 v[48:49], v[48:49], v[190:191]
	v_pk_add_f32 v[50:51], v[50:51], v[192:193]
	v_cvt_pk_bf16_f32 v172, v52, v53
	v_cvt_pk_bf16_f32 v173, v54, v55
	v_cvt_pk_bf16_f32 v174, v48, v49
	v_cvt_pk_bf16_f32 v175, v50, v51
	global_store_dwordx4 v[176:177], v[172:175], off
	v_mul_f32_e32 v53, v53, v53
	v_fmac_f32_e32 v53, v52, v52
	v_mul_f32_e32 v55, v55, v55
	v_fmac_f32_e32 v55, v54, v54
	v_mul_f32_e32 v49, v49, v49
	v_fmac_f32_e32 v49, v48, v48
	v_mul_f32_e32 v51, v51, v51
	v_fmac_f32_e32 v51, v50, v50
	v_add_f32_e32 v52, v53, v55
	v_add_f32_e32 v52, v52, v49
	v_add_f32_e32 v52, v51, v52
	v_add_f32_e32 v170, v60, v52
	ds_bpermute_b32 v171, v168, v170
	s_waitcnt lgkmcnt(0)
	v_add_f32_e32 v170, v170, v171
	ds_bpermute_b32 v171, v169, v170
	s_mov_b64 s[98:99], 0x10000
	v_lshl_add_u64 v[164:165], v[164:165], 0, s[98:99]
	v_lshl_add_u64 v[176:177], v[176:177], 0, s[98:99]
	s_and_saveexec_b64 s[34:35], s[0:1]
	s_waitcnt lgkmcnt(0)
	v_add_f32_e32 v170, v170, v171
	global_atomic_add_f32 v[166:167], v170, off offset:512
	s_or_b64 exec, exec, s[34:35]
	s_waitcnt vmcnt(17)
	v_pk_add_f32 v[44:45], v[44:45], v[194:195]
	v_pk_add_f32 v[46:47], v[46:47], v[196:197]
	v_pk_add_f32 v[40:41], v[40:41], v[198:199]
	v_pk_add_f32 v[42:43], v[42:43], v[200:201]
	v_cvt_pk_bf16_f32 v172, v44, v45
	v_cvt_pk_bf16_f32 v173, v46, v47
	v_cvt_pk_bf16_f32 v174, v40, v41
	v_cvt_pk_bf16_f32 v175, v42, v43
	global_store_dwordx4 v[164:165], v[172:175], off
	v_mul_f32_e32 v45, v45, v45
	v_fmac_f32_e32 v45, v44, v44
	v_mul_f32_e32 v47, v47, v47
	v_fmac_f32_e32 v47, v46, v46
	v_mul_f32_e32 v41, v41, v41
	v_fmac_f32_e32 v41, v40, v40
	v_mul_f32_e32 v43, v43, v43
	v_fmac_f32_e32 v43, v42, v42
	v_add_f32_e32 v44, v45, v47
	v_add_f32_e32 v44, v44, v41
	v_add_f32_e32 v44, v43, v44
	v_pk_add_f32 v[36:37], v[36:37], v[202:203]
	v_pk_add_f32 v[38:39], v[38:39], v[204:205]
	v_pk_add_f32 v[32:33], v[32:33], v[206:207]
	v_pk_add_f32 v[34:35], v[34:35], v[208:209]
	v_cvt_pk_bf16_f32 v172, v36, v37
	v_cvt_pk_bf16_f32 v173, v38, v39
	v_cvt_pk_bf16_f32 v174, v32, v33
	v_cvt_pk_bf16_f32 v175, v34, v35
	global_store_dwordx4 v[176:177], v[172:175], off
	v_mul_f32_e32 v37, v37, v37
	v_fmac_f32_e32 v37, v36, v36
	v_mul_f32_e32 v39, v39, v39
	v_fmac_f32_e32 v39, v38, v38
	v_mul_f32_e32 v33, v33, v33
	v_fmac_f32_e32 v33, v32, v32
	v_mul_f32_e32 v35, v35, v35
	v_fmac_f32_e32 v35, v34, v34
	v_add_f32_e32 v36, v37, v39
	v_add_f32_e32 v36, v36, v33
	v_add_f32_e32 v36, v35, v36
	v_add_f32_e32 v170, v44, v36
	ds_bpermute_b32 v171, v168, v170
	s_waitcnt lgkmcnt(0)
	v_add_f32_e32 v170, v170, v171
	ds_bpermute_b32 v171, v169, v170
	s_mov_b64 s[98:99], 0x10000
	v_lshl_add_u64 v[164:165], v[164:165], 0, s[98:99]
	v_lshl_add_u64 v[176:177], v[176:177], 0, s[98:99]
	s_and_saveexec_b64 s[34:35], s[0:1]
	s_waitcnt lgkmcnt(0)
; __device__ __forceinline__ u32x4 pack8(const f32x4 a, const f32x4 b) { u32x4 w; w.x = cvt_pk_bf16(a[0], a[1]); w.y = cvt_pk_bf16(a[2], a[3]); w.z = cvt_pk_bf16(b[0], b[1]); w.w = cvt_pk_bf16(b[2], b[3]); return w; }
;     __device__ __forceinline__ void operator()(AccRef acc, const Unit& u, int wr, int wc, int fr, int fq) const {
;         const float* xb = (u.pm < 128) ? xp : xs - (size_t)NPROMPT * D;
; #pragma unroll
;         for (int ai = 0; ai < 2; ++ai)
; #pragma unroll
;             for (int m = 0; m < 4; ++m) { const int row = u.pm * 256 + ai * 128 + wr * 64 + m * 16 + fr; float sq = 0.f;
; #pragma unroll
;                 for (int bj = 0; bj < 2; ++bj) { const size_t off = (size_t)row * D + u.pn * 256 + bj * 128 + wc * 32 + 8 * fq;
;                     const f32x4 a0 = *(const f32x4*)(xb + off) + acc[ai][bj][m][0], a1 = *(const f32x4*)(xb + off + 4) + acc[ai][bj][m][1];
;                     *(u32x4*)(X1B + off) = pack8(a0, a1);
;                     sq += (a0[0] * a0[0] + a0[1] * a0[1]) + (a0[2] * a0[2] + a0[3] * a0[3]) + (a1[0] * a1[0] + a1[1] * a1[1]) + (a1[2] * a1[2] + a1[3] * a1[3]); }
;                 sq += __shfl_xor(sq, 16); sq += __shfl_xor(sq, 32);
;                 if (fq == 0) atomicAdd(ssq + row, sq); }
	v_add_f32_e32 v170, v170, v171
	global_atomic_add_f32 v[166:167], v170, off offset:576
	s_or_b64 exec, exec, s[34:35]
	s_waitcnt vmcnt(13)
	v_pk_add_f32 v[28:29], v[28:29], v[210:211]
	v_pk_add_f32 v[30:31], v[30:31], v[212:213]
	v_pk_add_f32 v[24:25], v[24:25], v[214:215]
	v_pk_add_f32 v[26:27], v[26:27], v[216:217]
	v_cvt_pk_bf16_f32 v172, v28, v29
	v_cvt_pk_bf16_f32 v173, v30, v31
	v_cvt_pk_bf16_f32 v174, v24, v25
	v_cvt_pk_bf16_f32 v175, v26, v27
	global_store_dwordx4 v[164:165], v[172:175], off
	v_mul_f32_e32 v29, v29, v29
	v_fmac_f32_e32 v29, v28, v28
	v_mul_f32_e32 v31, v31, v31
	v_fmac_f32_e32 v31, v30, v30
	v_mul_f32_e32 v25, v25, v25
	v_fmac_f32_e32 v25, v24, v24
	v_mul_f32_e32 v27, v27, v27
	v_fmac_f32_e32 v27, v26, v26
	v_add_f32_e32 v28, v29, v31
	v_add_f32_e32 v28, v28, v25
	v_add_f32_e32 v28, v27, v28
	v_pk_add_f32 v[20:21], v[20:21], v[218:219]
	v_pk_add_f32 v[22:23], v[22:23], v[220:221]
	v_pk_add_f32 v[16:17], v[16:17], v[222:223]
	v_pk_add_f32 v[18:19], v[18:19], v[224:225]
	v_cvt_pk_bf16_f32 v172, v20, v21
	v_cvt_pk_bf16_f32 v173, v22, v23
	v_cvt_pk_bf16_f32 v174, v16, v17
	v_cvt_pk_bf16_f32 v175, v18, v19
	global_store_dwordx4 v[176:177], v[172:175], off
	v_mul_f32_e32 v21, v21, v21
	v_fmac_f32_e32 v21, v20, v20
	v_mul_f32_e32 v23, v23, v23
	v_fmac_f32_e32 v23, v22, v22
	v_mul_f32_e32 v17, v17, v17
	v_fmac_f32_e32 v17, v16, v16
	v_mul_f32_e32 v19, v19, v19
	v_fmac_f32_e32 v19, v18, v18
	v_add_f32_e32 v20, v21, v23
	v_add_f32_e32 v20, v20, v17
	v_add_f32_e32 v20, v19, v20
	v_add_f32_e32 v170, v28, v20
	ds_bpermute_b32 v171, v168, v170
	s_waitcnt lgkmcnt(0)
	v_add_f32_e32 v170, v170, v171
	ds_bpermute_b32 v171, v169, v170
	s_mov_b64 s[98:99], 0x10000
	v_lshl_add_u64 v[164:165], v[164:165], 0, s[98:99]
	v_lshl_add_u64 v[176:177], v[176:177], 0, s[98:99]
	s_and_saveexec_b64 s[34:35], s[0:1]
	s_waitcnt lgkmcnt(0)
	v_add_f32_e32 v170, v170, v171
	global_atomic_add_f32 v[166:167], v170, off offset:640
	s_or_b64 exec, exec, s[34:35]
	s_waitcnt vmcnt(9)
	v_pk_add_f32 v[12:13], v[12:13], v[226:227]
	v_pk_add_f32 v[14:15], v[14:15], v[228:229]
	v_pk_add_f32 v[8:9], v[8:9], v[230:231]
	v_pk_add_f32 v[10:11], v[10:11], v[232:233]
	v_cvt_pk_bf16_f32 v172, v12, v13
	v_cvt_pk_bf16_f32 v173, v14, v15
	v_cvt_pk_bf16_f32 v174, v8, v9
	v_cvt_pk_bf16_f32 v175, v10, v11
	global_store_dwordx4 v[164:165], v[172:175], off
	v_mul_f32_e32 v13, v13, v13
	v_fmac_f32_e32 v13, v12, v12
	v_mul_f32_e32 v15, v15, v15
	v_fmac_f32_e32 v15, v14, v14
	v_mul_f32_e32 v9, v9, v9
	v_fmac_f32_e32 v9, v8, v8
	v_mul_f32_e32 v11, v11, v11
	v_fmac_f32_e32 v11, v10, v10
	v_add_f32_e32 v12, v13, v15
	v_add_f32_e32 v12, v12, v9
	v_add_f32_e32 v12, v11, v12
	v_pk_add_f32 v[4:5], v[4:5], v[234:235]
	v_pk_add_f32 v[6:7], v[6:7], v[236:237]
	v_pk_add_f32 v[0:1], v[0:1], v[238:239]
	v_pk_add_f32 v[2:3], v[2:3], v[240:241]
	v_cvt_pk_bf16_f32 v172, v4, v5
	v_cvt_pk_bf16_f32 v173, v6, v7
	v_cvt_pk_bf16_f32 v174, v0, v1
	v_cvt_pk_bf16_f32 v175, v2, v3
	global_store_dwordx4 v[176:177], v[172:175], off
	v_mul_f32_e32 v5, v5, v5
	v_fmac_f32_e32 v5, v4, v4
	v_mul_f32_e32 v7, v7, v7
	v_fmac_f32_e32 v7, v6, v6
	v_mul_f32_e32 v1, v1, v1
	v_fmac_f32_e32 v1, v0, v0
	v_mul_f32_e32 v3, v3, v3
	v_fmac_f32_e32 v3, v2, v2
	v_add_f32_e32 v4, v5, v7
	v_add_f32_e32 v4, v4, v1
	v_add_f32_e32 v4, v3, v4
	v_add_f32_e32 v170, v12, v4
	ds_bpermute_b32 v171, v168, v170
	s_waitcnt lgkmcnt(0)
	v_add_f32_e32 v170, v170, v171
	ds_bpermute_b32 v171, v169, v170
	s_and_saveexec_b64 s[34:35], s[0:1]
	s_waitcnt lgkmcnt(0)
	v_add_f32_e32 v170, v170, v171
	global_atomic_add_f32 v[166:167], v170, off offset:704
	s_or_b64 exec, exec, s[34:35]
	s_cmpk_lt_i32 s38, 0x80
	s_cbranch_scc0 .LBB0_745

;     __device__ bool next(int i, Unit& u) const { return at((long)i * G + c, u); }
;     __device__ bool next(int i, Unit& u) const { if (i > 0) return false; u.pm = pm; u.pn = pn; u.g = 0; u.nt = nt; u.k0 = 0; u.part = -1; return true; }
; #define PG8_STAGE(bufoff, gbase, voff) do { _Pragma("unroll") for (int _i = 0; _i < 2; ++_i) \
;         __builtin_amdgcn_global_load_lds((const unsigned*)((const char*)(gbase) + (voff)[_i]), (LAS unsigned*)(lds + (bufoff) + ldsw + _i * 8192), 16, 0, 0); } while (0)
; #define PG8_WAIT_V(n) asm volatile("s_waitcnt vmcnt(" #n ")" ::: "memory")
; template <class Epi, class Sched>
; __device__ __forceinline__ void gemm_phase(LAS unsigned char* lds, const Gemm g, const Sched& S, const Epi& E) {
;     const int tid = threadIdx.x, wid = __builtin_amdgcn_readfirstlane(tid >> 6), lane = tid & 63, wr = wid >> 2, wc = wid & 3, fr = lane & 15, fq = lane >> 4;
;     unsigned voffA[2], voffB[2];
; #pragma unroll
;     for (int i = 0; i < 2; ++i) { int R, C; stage_rc(tid * 16 + i * 8192, R, C); const int Rb = Epi::PERM ? ((R & ~31) + perm32(R & 31)) : R;
;         voffA[i] = (unsigned)(R * g.lda + C) * 2u; voffB[i] = (unsigned)(Rb * g.ldb + C) * 2u; }
;     const size_t kstep = (size_t)(BK * 2);
;     const size_t hstepA = (size_t)HALF * g.lda * 2, hstepB = (size_t)HALF * g.ldb * 2;
;     const unsigned ldsw = (unsigned)wid * 1024u;
;     const int aoff = lds_byte(wr * 64 + fr, fq * 8), boff = lds_byte(wc * 32 + fr, fq * 8);
;     ...
;     Unit cur, nxt; int ui = 0;
;     if (!S.next(0, cur)) return;
;     f32x4 acc[2][2][4][2];
; #pragma unroll
;     for (int a = 0; a < 2; ++a)
; #pragma unroll
;         for (int b = 0; b < 2; ++b)
; #pragma unroll
;             for (int m = 0; m < 4; ++m)
; #pragma unroll
;                 for (int n = 0; n < 2; ++n) acc[a][b][m][n] = (f32x4){0.f, 0.f, 0.f, 0.f};
;     bf16x8 At[4][2], B0[2][2], B1[2][2];
;     const char* cA = PG8_ABASE(cur); const char* cB = PG8_BBASE(cur);
;     PG8_STAGE(PG8_SB(0, 0), cB, voffB); PG8_STAGE(PG8_SB(0, 1), cB + hstepB, voffB); PG8_STAGE(PG8_SA(0, 0), cA, voffA); PG8_STAGE(PG8_SA(0, 1), cA + hstepA, voffA);
;     if (wr == 1) PG8_BAR;
;     PG8_WAIT_V(2); PG8_BAR;
;     PG8_STAGE(PG8_SB(1, 0), cB + kstep, voffB); PG8_STAGE(PG8_SA(1, 0), cA + kstep, voffA); PG8_STAGE(PG8_SB(1, 1), cB + hstepB + kstep, voffB);
;     PG8_WAIT_V(6); PG8_BAR;
.LBB0_825:
	s_add_i32 s0, s8, s0
	s_ashr_i32 s8, s0, 31
	s_lshr_b32 s8, s8, 24
	s_add_i32 s8, s0, s8
	s_ashr_i32 s9, s8, 8
	s_and_b32 s8, s8, 0xff00
	s_sub_i32 s8, s0, s8
	v_lshrrev_b32_e32 v2, 1, v136
	s_sext_i32_i16 s0, s8
	v_and_b32_e32 v11, 24, v2
	v_lshrrev_b32_e32 v2, 5, v136
	s_bfe_u32 s0, s0, 0x3001c
	v_and_b32_e32 v2, 4, v2
	v_bfe_u32 v3, v136, 2, 2
	s_add_i32 s10, s8, s0
	v_lshlrev_b32_e32 v0, 4, v136
	s_waitcnt lgkmcnt(0)
	v_and_b32_e32 v1, 32, v136
	v_bfe_u32 v10, v136, 2, 4
	v_or3_b32 v2, v2, v3, v11
	v_lshrrev_b32_e32 v3, 3, v136
	s_movk_i32 s2, 0x70
	s_sext_i32_i16 s0, s10
	s_and_b32 s10, s10, 0xfff8
	v_bitop3_b32 v8, v0, v1, 48 bitop3:0x6c
	v_and_b32_e32 v9, 64, v136
	v_and_or_b32 v4, v3, s2, v10
	s_movk_i32 s2, 0x60
	v_add_u32_e32 v12, 0x2000, v0
	s_sub_i32 s8, s8, s10
	v_or_b32_e32 v1, v8, v9
	v_and_or_b32 v3, v3, s2, v2
	v_lshrrev_b32_e32 v0, 7, v12
	s_movk_i32 s2, 0xf0
	s_lshl_b32 s9, s9, 3
	s_sext_i32_i16 s8, s8
	s_lshr_b32 s1, s12, 8
	v_lshl_or_b32 v130, v3, 12, v1
	v_and_or_b32 v3, v0, s2, v10
	s_movk_i32 s2, 0xe0
	s_lshr_b32 s0, s0, 3
	s_add_i32 s24, s9, s8
	v_and_or_b32 v0, v0, s2, v2
	s_lshr_b32 s2, s12, 6
	s_ashr_i32 s25, s24, 31
	s_bfe_i64 s[10:11], s[0:1], 0x100000
	s_lshl_b32 s5, s2, 10
	s_lshl_b64 s[8:9], s[24:25], 20
	s_lshl_b64 s[10:11], s[10:11], 20
	s_add_u32 s38, s88, s10
	s_addc_u32 s39, s89, s11
	s_add_i32 s25, s5, 0
	s_add_i32 m0, s25, 0x10000
	v_lshl_or_b32 v134, v0, 12, v1
	global_load_lds_dwordx4 v130, s[38:39]
	s_add_i32 m0, s25, 0x12000
	s_add_u32 s10, s38, 0x80000
	global_load_lds_dwordx4 v134, s[38:39]
	s_addc_u32 s11, s39, 0
	s_add_i32 m0, s25, 0x14000
	v_lshl_or_b32 v128, v4, 12, v1
	v_and_b32_e32 v238, 0x70000, v128
	v_and_b32_e32 v239, 64, v128
	v_lshl_or_b32 v238, v239, 4, v238
	v_and_b32_e32 v239, 63, v136
	v_lshl_or_b32 v128, v239, 4, v238
	global_load_lds_dwordx4 v130, s[10:11]
	s_add_i32 m0, s25, 0x16000
	s_add_u32 s36, s14, s8
	s_addc_u32 s37, s15, s9
	s_add_i32 s33, s25, 0x2000
	global_load_lds_dwordx4 v134, s[10:11]
	s_mov_b32 m0, s25
	s_add_u32 s8, s36, 0x80000
	v_lshl_or_b32 v132, v3, 12, v1
	v_and_b32_e32 v238, 0x70000, v132
	v_and_b32_e32 v239, 64, v132
	v_lshl_or_b32 v238, v239, 4, v238
	v_and_b32_e32 v239, 63, v136
	v_lshl_or_b32 v132, v239, 4, v238
	global_load_lds_dwordx4 v128, s[36:37]
	s_mov_b32 m0, s33
	s_addc_u32 s9, s37, 0
	s_add_i32 s34, s25, 0x4000
	global_load_lds_dwordx4 v132, s[36:37]
	s_mov_b32 m0, s34
	s_add_i32 s35, s25, 0x6000
	global_load_lds_dwordx4 v128, s[8:9]
	s_mov_b32 m0, s35
	v_mov_b32_e32 v131, 0
	global_load_lds_dwordx4 v132, s[8:9]
	v_mov_b32_e32 v135, v131
	v_mov_b32_e32 v129, v131
	v_mov_b32_e32 v133, v131
	s_cmp_eq_u32 s1, 1
	s_mov_b32 s42, 0
	v_lshl_add_u64 v[6:7], s[38:39], 0, v[130:131]
	v_lshl_add_u64 v[4:5], s[38:39], 0, v[134:135]
	v_lshl_add_u64 v[0:1], s[36:37], 0, v[128:129]
	s_cselect_b64 s[8:9], -1, 0
	s_cmp_lg_u32 s1, 1
	v_lshl_add_u64 v[2:3], s[36:37], 0, v[132:133]
	s_cbranch_scc1 .LBB0_827
	s_barrier
.LBB0_827:
	s_lshl_b32 s2, s2, 5
	s_mov_b64 s[10:11], 0x80
	s_mov_b64 s[98:99], 0x800
	s_and_b32 s18, s2, 0x60
	s_add_i32 m0, s25, 0x18000
	v_lshl_add_u64 v[6:7], v[6:7], 0, s[10:11]
	s_lshl_b32 s13, s1, 13
	s_lshl_b32 s19, s18, 7
	s_waitcnt vmcnt(2)
	s_barrier
	global_load_lds_dwordx4 v[6:7], off
	v_lshl_add_u64 v[4:5], v[4:5], 0, s[10:11]
	s_add_i32 m0, s25, 0x1a000
	s_add_i32 s43, s25, 0x8000
	s_add_i32 s44, s25, 0xa000
	global_load_lds_dwordx4 v[4:5], off
	v_lshl_add_u64 v[0:1], v[0:1], 0, s[98:99]
	s_mov_b32 m0, s43
	s_add_u32 s16, s38, 0x80080
	global_load_lds_dwordx4 v[0:1], off
	v_lshl_add_u64 v[0:1], v[2:3], 0, s[98:99]
	s_mov_b32 m0, s44
	s_addc_u32 s17, s39, 0
	global_load_lds_dwordx4 v[0:1], off
	s_add_i32 m0, s25, 0x1c000
	v_lshl_add_u64 v[0:1], s[16:17], 0, v[130:131]
	global_load_lds_dwordx4 v[0:1], off
	v_lshl_add_u64 v[0:1], s[16:17], 0, v[134:135]
	s_add_i32 m0, s25, 0x1e000
	s_sext_i32_i16 s2, s0
	global_load_lds_dwordx4 v[0:1], off
	v_and_b32_e32 v0, 15, v136
	v_lshlrev_b32_e32 v1, 1, v11
	v_lshlrev_b32_e32 v2, 2, v136
	v_lshlrev_b32_e32 v3, 6, v136
	s_movk_i32 s0, 0x3c0
	v_lshl_or_b32 v137, s1, 6, v0
	v_lshl_or_b32 v0, v0, 6, v1
	v_and_b32_e32 v2, 32, v2
	v_and_or_b32 v1, v3, s0, v1
	v_bitop3_b32 v153, s19, v1, v2 bitop3:0xf6
	v_lshlrev_b32_e32 v1, 9, v136
	v_bitop3_b32 v0, v0, s13, v2 bitop3:0xde
	v_and_b32_e32 v1, 0x70000, v1
	v_lshlrev_b32_e32 v2, 12, v10
	v_or3_b32 v1, v8, v1, v2
	v_add_u32_e32 v138, v1, v9
	v_and_b32_e32 v238, 0x70000, v138
	v_and_b32_e32 v239, 64, v138
	v_lshl_or_b32 v238, v239, 4, v238
	v_and_b32_e32 v239, 63, v136
	v_lshl_or_b32 v138, v239, 4, v238
	v_lshlrev_b32_e32 v1, 5, v12
	s_waitcnt vmcnt(6)
	s_cmpk_lt_u32 s12, 0x100
	v_and_b32_e32 v1, 0xf0000, v1
	s_cselect_b64 s[12:13], -1, 0
	v_or3_b32 v1, v8, v1, v2
	s_add_i32 s46, 0, 0x10000
	s_add_i32 s47, 0, 0x14000
	s_ashr_i32 s45, s3, 31
	v_or_b32_e32 v154, s18, v11
	v_mov_b32_e32 v139, v131
	v_add_u32_e32 v140, v1, v9
	v_and_b32_e32 v238, 0x70000, v140
	v_and_b32_e32 v239, 64, v140
	v_lshl_or_b32 v238, v239, 4, v238
	v_and_b32_e32 v239, 63, v136
	v_lshl_or_b32 v140, v239, 4, v238
	v_mov_b32_e32 v141, v131
	v_mov_b64_e32 v[142:143], 0x1000
	v_mov_b64_e32 v[144:145], 0xfff
	v_add_u32_e32 v155, s46, v153
	v_add_u32_e32 v156, s47, v153
	v_and_b32_e32 v157, 0xffffe000, v0
	v_and_b32_e32 v238, 63, v136
	v_lshl_or_b32 v157, v238, 4, v157
	v_mov_b32_e32 v158, 0x358637bd
	s_mov_b32 s50, 0x800000
	s_barrier
	s_branch .LBB0_830

;     __device__ bool next(int i, Unit& u) const { return at((long)i * G + c, u); }
;     __device__ bool next(int i, Unit& u) const { if (i > 0) return false; u.pm = pm; u.pn = pn; u.g = 0; u.nt = nt; u.k0 = 0; u.part = -1; return true; }
; #define PG8_STAGE(bufoff, gbase, voff) do { _Pragma("unroll") for (int _i = 0; _i < 2; ++_i) \
;         __builtin_amdgcn_global_load_lds((const unsigned*)((const char*)(gbase) + (voff)[_i]), (LAS unsigned*)(lds + (bufoff) + ldsw + _i * 8192), 16, 0, 0); } while (0)
; #define PG8_LDA(dst, b, h) do { _Pragma("unroll") for (int m = 0; m < 4; ++m) _Pragma("unroll") for (int k = 0; k < 2; ++k) dst[m][k] = *(const LAS bf16x8*)(lds + PG8_SA(b, h) + aoff + m * 2048 + k * 1024); } while (0)
; #define PG8_LDB(dst, b, h) do { _Pragma("unroll") for (int n = 0; n < 2; ++n) _Pragma("unroll") for (int k = 0; k < 2; ++k) dst[n][k] = *(const LAS bf16x8*)(lds + PG8_SB(b, h) + boff + n * 2048 + k * 1024); } while (0)
; #define PG8_WAIT_V(n) asm volatile("s_waitcnt vmcnt(" #n ")" ::: "memory")
; #define PG8_WAIT_L(n) asm volatile("s_waitcnt lgkmcnt(" #n ")" ::: "memory")
; template <class Epi, class Sched>
; __device__ __forceinline__ void gemm_phase(LAS unsigned char* lds, const Gemm g, const Sched& S, const Epi& E) {
;     ...
;         const bool has_next = S.next(ui + 1, nxt);
;         const char* nA = has_next ? PG8_ABASE(nxt) : cA; const char* nB = has_next ? PG8_BBASE(nxt) : cB;
;         const int nt = cur.nt;
;         for (int t = 0; t < nt; t += 2) {
;             const bool last = (t == nt - 2);
;             const char* a1 = cA + (size_t)(t + 1) * kstep;
;             const char* a2 = last ? nA : cA + (size_t)(t + 2) * kstep; const char* b2 = last ? nB : cB + (size_t)(t + 2) * kstep;
;             const char* a3 = a2 + kstep; const char* b3 = b2 + kstep;
;             PG8_LDB(B0, 0, 0); PG8_LDB(B1, 0, 1); PG8_SCHED; PG8_LDA(At, 0, 0); PG8_STAGE(PG8_SA(1, 1), a1 + hstepA, voffA);
;             PG8_WAIT_V(8); PG8_WAIT_L(0); PG8_BAR; PG8_MMA(0, 0, At, B0); PG8_MMA(0, 1, At, B1); PG8_BAR; PG8_SCHED;
;     ...
; #pragma unroll
;         for (int a = 0; a < 2; ++a)
; #pragma unroll
;             for (int b = 0; b < 2; ++b)
; #pragma unroll
;                 for (int m = 0; m < 4; ++m)
; #pragma unroll
;                     for (int n = 0; n < 2; ++n) acc[a][b][m][n] = (f32x4){0.f, 0.f, 0.f, 0.f};
;         cur = nxt; cA = nA; cB = nB; ++ui;
.LBB0_836:
	s_ashr_i32 s19, s18, 31
	s_lshl_b64 s[20:21], s[18:19], 20
	s_add_u32 s20, s14, s20
	s_addc_u32 s21, s15, s21
	s_and_b64 s[22:23], s[0:1], exec
	s_cselect_b32 s19, s21, s37
	s_cselect_b32 s51, s20, s36
	s_ashr_i32 s17, s16, 31
	s_lshl_b64 s[22:23], s[16:17], 20
	s_add_u32 s22, s88, s22
	s_addc_u32 s23, s89, s23
	s_and_b64 s[40:41], s[0:1], exec
	s_cselect_b32 s17, s23, s39
	s_cselect_b32 s52, s22, s38
	s_add_u32 s36, s36, 0x80800
	s_addc_u32 s37, s37, 0
	s_add_u32 s53, s38, 0x100
	v_mov_b32_e32 v0, 0
	s_addc_u32 s54, s39, 0
	s_mov_b32 s55, -2
	v_mov_b32_e32 v1, v0
	v_mov_b32_e32 v2, v0
	v_mov_b32_e32 v3, v0
	v_mov_b32_e32 v4, v0
	v_mov_b32_e32 v5, v0
	v_mov_b32_e32 v6, v0
	v_mov_b32_e32 v7, v0
	v_mov_b32_e32 v16, v0
	v_mov_b32_e32 v17, v0
	v_mov_b32_e32 v18, v0
	v_mov_b32_e32 v19, v0
	v_mov_b32_e32 v20, v0
	v_mov_b32_e32 v21, v0
	v_mov_b32_e32 v22, v0
	v_mov_b32_e32 v23, v0
	s_waitcnt vmcnt(0)
	v_mov_b32_e32 v32, v0
	v_mov_b32_e32 v33, v0
	v_mov_b32_e32 v34, v0
	v_mov_b32_e32 v35, v0
	v_mov_b32_e32 v36, v0
	v_mov_b32_e32 v37, v0
	v_mov_b32_e32 v38, v0
	v_mov_b32_e32 v39, v0
	v_mov_b32_e32 v48, v0
	v_mov_b32_e32 v49, v0
	v_mov_b32_e32 v50, v0
	v_mov_b32_e32 v51, v0
	v_mov_b32_e32 v52, v0
	v_mov_b32_e32 v53, v0
	v_mov_b32_e32 v54, v0
	v_mov_b32_e32 v55, v0
	v_mov_b32_e32 v8, v0
	v_mov_b32_e32 v9, v0
	v_mov_b32_e32 v10, v0
	v_mov_b32_e32 v11, v0
	v_mov_b32_e32 v12, v0
	v_mov_b32_e32 v13, v0
	v_mov_b32_e32 v14, v0
	v_mov_b32_e32 v15, v0
	v_mov_b32_e32 v24, v0
	v_mov_b32_e32 v25, v0
	v_mov_b32_e32 v26, v0
	v_mov_b32_e32 v27, v0
	v_mov_b32_e32 v28, v0
	v_mov_b32_e32 v29, v0
	v_mov_b32_e32 v30, v0
	v_mov_b32_e32 v31, v0
	v_mov_b32_e32 v40, v0
	v_mov_b32_e32 v41, v0
	v_mov_b32_e32 v42, v0
	v_mov_b32_e32 v43, v0
	v_mov_b32_e32 v44, v0
	v_mov_b32_e32 v45, v0
	v_mov_b32_e32 v46, v0
	v_mov_b32_e32 v47, v0
	v_mov_b32_e32 v56, v0
	v_mov_b32_e32 v57, v0
	v_mov_b32_e32 v58, v0
	v_mov_b32_e32 v59, v0
	v_mov_b32_e32 v60, v0
	v_mov_b32_e32 v61, v0
	v_mov_b32_e32 v62, v0
	v_mov_b32_e32 v63, v0
	v_mov_b32_e32 v64, v0
	v_mov_b32_e32 v65, v0
	v_mov_b32_e32 v66, v0
	v_mov_b32_e32 v67, v0
	v_mov_b32_e32 v68, v0
	v_mov_b32_e32 v69, v0
	v_mov_b32_e32 v70, v0
	v_mov_b32_e32 v71, v0
	v_mov_b32_e32 v80, v0
	v_mov_b32_e32 v81, v0
	v_mov_b32_e32 v82, v0
	v_mov_b32_e32 v83, v0
	v_mov_b32_e32 v84, v0
	v_mov_b32_e32 v85, v0
	v_mov_b32_e32 v86, v0
	v_mov_b32_e32 v87, v0
	v_mov_b32_e32 v96, v0
	v_mov_b32_e32 v97, v0
	v_mov_b32_e32 v98, v0
	v_mov_b32_e32 v99, v0
	v_mov_b32_e32 v100, v0
	v_mov_b32_e32 v101, v0
	v_mov_b32_e32 v102, v0
	v_mov_b32_e32 v103, v0
	v_mov_b32_e32 v112, v0
	v_mov_b32_e32 v113, v0
	v_mov_b32_e32 v114, v0
	v_mov_b32_e32 v115, v0
	v_mov_b32_e32 v116, v0
	v_mov_b32_e32 v117, v0
	v_mov_b32_e32 v118, v0
	v_mov_b32_e32 v119, v0
	v_mov_b32_e32 v72, v0
	v_mov_b32_e32 v73, v0
	v_mov_b32_e32 v74, v0
	v_mov_b32_e32 v75, v0
	v_mov_b32_e32 v76, v0
	v_mov_b32_e32 v77, v0
	v_mov_b32_e32 v78, v0
	v_mov_b32_e32 v79, v0
	v_mov_b32_e32 v88, v0
	v_mov_b32_e32 v89, v0
	v_mov_b32_e32 v90, v0
	v_mov_b32_e32 v91, v0
	v_mov_b32_e32 v92, v0
	v_mov_b32_e32 v93, v0
	v_mov_b32_e32 v94, v0
	v_mov_b32_e32 v95, v0
	v_mov_b32_e32 v104, v0
	v_mov_b32_e32 v105, v0
	v_mov_b32_e32 v106, v0
	v_mov_b32_e32 v107, v0
	v_mov_b32_e32 v108, v0
	v_mov_b32_e32 v109, v0
	v_mov_b32_e32 v110, v0
	v_mov_b32_e32 v111, v0
	v_mov_b32_e32 v120, v0
	v_mov_b32_e32 v121, v0
	v_mov_b32_e32 v122, v0
	v_mov_b32_e32 v123, v0
	v_mov_b32_e32 v124, v0
	v_mov_b32_e32 v125, v0
	v_mov_b32_e32 v126, v0
	v_mov_b32_e32 v127, v0
.LBB0_837:
	ds_read_b128 v[146:149], v155
	ds_read_b128 v[160:163], v155 offset:1024
	ds_read_b128 v[164:167], v155 offset:2048
	ds_read_b128 v[168:171], v155 offset:3072
	ds_read_b128 v[172:175], v156
	ds_read_b128 v[176:179], v156 offset:1024
	ds_read_b128 v[180:183], v156 offset:2048
	ds_read_b128 v[184:187], v156 offset:3072
	s_add_u32 s38, s36, 0xfff80800
	s_addc_u32 s39, s37, -1
	s_cmp_eq_u32 s55, 28
	s_cselect_b32 s41, s19, s39
	s_cselect_b32 s40, s51, s38
	s_cselect_b32 s39, s17, s54
	s_cselect_b32 s38, s52, s53
	v_lshl_add_u64 v[150:151], s[36:37], 0, v[138:139]
	s_add_i32 m0, s25, 0xc000
	ds_read_b128 v[188:191], v157
	ds_read_b128 v[192:195], v157 offset:1024
	ds_read_b128 v[196:199], v157 offset:2048
	ds_read_b128 v[200:203], v157 offset:3072
	ds_read_b128 v[204:207], v157 offset:4096
	ds_read_b128 v[208:211], v157 offset:5120
	ds_read_b128 v[212:215], v157 offset:6144
	ds_read_b128 v[216:219], v157 offset:7168
	global_load_lds_dwordx4 v[150:151], off
	v_lshl_add_u64 v[150:151], s[36:37], 0, v[140:141]
	s_add_i32 m0, s25, 0xe000
	s_nop 0
	global_load_lds_dwordx4 v[150:151], off
	s_waitcnt vmcnt(8)
	s_waitcnt lgkmcnt(0)
	s_barrier
; #define PG8_STAGE(bufoff, gbase, voff) do { _Pragma("unroll") for (int _i = 0; _i < 2; ++_i) \
;         __builtin_amdgcn_global_load_lds((const unsigned*)((const char*)(gbase) + (voff)[_i]), (LAS unsigned*)(lds + (bufoff) + ldsw + _i * 8192), 16, 0, 0); } while (0)
; #define PG8_LDA(dst, b, h) do { _Pragma("unroll") for (int m = 0; m < 4; ++m) _Pragma("unroll") for (int k = 0; k < 2; ++k) dst[m][k] = *(const LAS bf16x8*)(lds + PG8_SA(b, h) + aoff + m * 2048 + k * 1024); } while (0)
; #define PG8_LDB(dst, b, h) do { _Pragma("unroll") for (int n = 0; n < 2; ++n) _Pragma("unroll") for (int k = 0; k < 2; ++k) dst[n][k] = *(const LAS bf16x8*)(lds + PG8_SB(b, h) + boff + n * 2048 + k * 1024); } while (0)
; #define PG8_MMA(ai, bj, At, Bt) do { __builtin_amdgcn_s_setprio(1); _Pragma("unroll") for (int m = 0; m < 4; ++m) _Pragma("unroll") for (int n = 0; n < 2; ++n) _Pragma("unroll") for (int k = 0; k < 2; ++k) \
;         acc[ai][bj][m][n] = __builtin_amdgcn_mfma_f32_16x16x32_bf16(Bt[n][k], At[m][k], acc[ai][bj][m][n], 0, 0, 0); __builtin_amdgcn_s_setprio(0); } while (0)
; #define PG8_WAIT_V(n) asm volatile("s_waitcnt vmcnt(" #n ")" ::: "memory")
; #define PG8_WAIT_L(n) asm volatile("s_waitcnt lgkmcnt(" #n ")" ::: "memory")
; #define PG8_BAR __builtin_amdgcn_s_barrier()
; #define PG8_SCHED __builtin_amdgcn_sched_barrier(0)
; template <class Epi, class Sched>
; __device__ __forceinline__ void gemm_phase(LAS unsigned char* lds, const Gemm g, const Sched& S, const Epi& E) {
;     ...
;             PG8_LDB(B0, 0, 0); PG8_LDB(B1, 0, 1); PG8_SCHED; PG8_LDA(At, 0, 0); PG8_STAGE(PG8_SA(1, 1), a1 + hstepA, voffA);
;             PG8_WAIT_V(8); PG8_WAIT_L(0); PG8_BAR; PG8_MMA(0, 0, At, B0); PG8_MMA(0, 1, At, B1); PG8_BAR; PG8_SCHED;
;             PG8_LDA(At, 0, 1); PG8_STAGE(PG8_SB(0, 0), b2, voffB); PG8_STAGE(PG8_SB(0, 1), b2 + hstepB, voffB); PG8_STAGE(PG8_SA(0, 0), a2, voffA);
;             PG8_WAIT_V(8); PG8_WAIT_L(0); PG8_BAR; PG8_MMA(1, 0, At, B0); PG8_MMA(1, 1, At, B1); PG8_BAR; PG8_SCHED;
;             PG8_LDB(B0, 1, 0); PG8_LDB(B1, 1, 1); PG8_SCHED; PG8_LDA(At, 1, 0); PG8_STAGE(PG8_SA(0, 1), a2 + hstepA, voffA);
;             PG8_WAIT_V(8); PG8_WAIT_L(0); PG8_BAR; PG8_MMA(0, 0, At, B0); PG8_MMA(0, 1, At, B1); PG8_BAR; PG8_SCHED;
	s_setprio 1
	s_waitcnt lgkmcnt(0)
	v_mfma_f32_16x16x32_bf16 v[124:127], v[146:149], v[188:191], v[124:127]
	v_mfma_f32_16x16x32_bf16 v[120:123], v[164:167], v[188:191], v[120:123]
	v_mfma_f32_16x16x32_bf16 v[108:111], v[146:149], v[196:199], v[108:111]
	v_mfma_f32_16x16x32_bf16 v[104:107], v[164:167], v[196:199], v[104:107]
	v_mfma_f32_16x16x32_bf16 v[92:95], v[146:149], v[204:207], v[92:95]
	v_mfma_f32_16x16x32_bf16 v[88:91], v[164:167], v[204:207], v[88:91]
	v_mfma_f32_16x16x32_bf16 v[76:79], v[146:149], v[212:215], v[76:79]
	v_mfma_f32_16x16x32_bf16 v[72:75], v[164:167], v[212:215], v[72:75]
	v_mfma_f32_16x16x32_bf16 v[124:127], v[160:163], v[192:195], v[124:127]
	v_mfma_f32_16x16x32_bf16 v[120:123], v[168:171], v[192:195], v[120:123]
	v_mfma_f32_16x16x32_bf16 v[108:111], v[160:163], v[200:203], v[108:111]
	v_mfma_f32_16x16x32_bf16 v[104:107], v[168:171], v[200:203], v[104:107]
	v_mfma_f32_16x16x32_bf16 v[92:95], v[160:163], v[208:211], v[92:95]
	v_mfma_f32_16x16x32_bf16 v[88:91], v[168:171], v[208:211], v[88:91]
	v_mfma_f32_16x16x32_bf16 v[76:79], v[160:163], v[216:219], v[76:79]
	v_mfma_f32_16x16x32_bf16 v[72:75], v[168:171], v[216:219], v[72:75]
	s_setprio 0
	s_setprio 1
	v_mfma_f32_16x16x32_bf16 v[116:119], v[172:175], v[188:191], v[116:119]
	v_mfma_f32_16x16x32_bf16 v[112:115], v[180:183], v[188:191], v[112:115]
	v_mfma_f32_16x16x32_bf16 v[100:103], v[172:175], v[196:199], v[100:103]
	v_mfma_f32_16x16x32_bf16 v[96:99], v[180:183], v[196:199], v[96:99]
	v_mfma_f32_16x16x32_bf16 v[84:87], v[172:175], v[204:207], v[84:87]
	v_mfma_f32_16x16x32_bf16 v[80:83], v[180:183], v[204:207], v[80:83]
	v_mfma_f32_16x16x32_bf16 v[68:71], v[172:175], v[212:215], v[68:71]
	v_mfma_f32_16x16x32_bf16 v[64:67], v[180:183], v[212:215], v[64:67]
	v_mfma_f32_16x16x32_bf16 v[116:119], v[176:179], v[192:195], v[116:119]
	v_mfma_f32_16x16x32_bf16 v[112:115], v[184:187], v[192:195], v[112:115]
	v_mfma_f32_16x16x32_bf16 v[100:103], v[176:179], v[200:203], v[100:103]
	v_mfma_f32_16x16x32_bf16 v[96:99], v[184:187], v[200:203], v[96:99]
	v_mfma_f32_16x16x32_bf16 v[84:87], v[176:179], v[208:211], v[84:87]
	v_mfma_f32_16x16x32_bf16 v[80:83], v[184:187], v[208:211], v[80:83]
	v_mfma_f32_16x16x32_bf16 v[68:71], v[176:179], v[216:219], v[68:71]
	v_mfma_f32_16x16x32_bf16 v[64:67], v[184:187], v[216:219], v[64:67]
	s_setprio 0
	s_barrier
	s_add_i32 s48, s46, s5
	v_lshl_add_u64 v[150:151], s[38:39], 0, v[130:131]
	s_mov_b32 m0, s48
	ds_read_b128 v[188:191], v157 offset:16384
	ds_read_b128 v[192:195], v157 offset:17408
	ds_read_b128 v[196:199], v157 offset:18432
	ds_read_b128 v[200:203], v157 offset:19456
	ds_read_b128 v[204:207], v157 offset:20480
	ds_read_b128 v[208:211], v157 offset:21504
	ds_read_b128 v[212:215], v157 offset:22528
	ds_read_b128 v[216:219], v157 offset:23552
	global_load_lds_dwordx4 v[150:151], off
	s_add_i32 m0, s48, 0x2000
	s_add_u32 s48, s38, 0x80000
	v_lshl_add_u64 v[220:221], s[38:39], 0, v[134:135]
	s_addc_u32 s49, s39, 0
	s_add_i32 s56, s47, s5
	global_load_lds_dwordx4 v[220:221], off
	v_lshl_add_u64 v[222:223], s[48:49], 0, v[130:131]
	s_mov_b32 m0, s56
	v_lshl_add_u64 v[224:225], s[40:41], 0, v[132:133]
	global_load_lds_dwordx4 v[222:223], off
	v_lshl_add_u64 v[222:223], s[48:49], 0, v[134:135]
	s_add_i32 m0, s56, 0x2000
	s_nop 0
	global_load_lds_dwordx4 v[222:223], off
	v_lshl_add_u64 v[222:223], s[40:41], 0, v[128:129]
	s_mov_b32 m0, s25
	s_nop 0
	global_load_lds_dwordx4 v[222:223], off
	s_mov_b32 m0, s33
	s_nop 0
	global_load_lds_dwordx4 v[224:225], off
	s_waitcnt vmcnt(8)
	s_waitcnt lgkmcnt(0)
	s_barrier
	s_setprio 1
	s_waitcnt lgkmcnt(0)
	v_mfma_f32_16x16x32_bf16 v[60:63], v[146:149], v[188:191], v[60:63]
	v_mfma_f32_16x16x32_bf16 v[56:59], v[164:167], v[188:191], v[56:59]
	v_mfma_f32_16x16x32_bf16 v[44:47], v[146:149], v[196:199], v[44:47]
	v_mfma_f32_16x16x32_bf16 v[40:43], v[164:167], v[196:199], v[40:43]
	v_mfma_f32_16x16x32_bf16 v[28:31], v[146:149], v[204:207], v[28:31]
	v_mfma_f32_16x16x32_bf16 v[24:27], v[164:167], v[204:207], v[24:27]
	v_mfma_f32_16x16x32_bf16 v[12:15], v[146:149], v[212:215], v[12:15]
	v_mfma_f32_16x16x32_bf16 v[8:11], v[164:167], v[212:215], v[8:11]
	v_mfma_f32_16x16x32_bf16 v[60:63], v[160:163], v[192:195], v[60:63]
	v_mfma_f32_16x16x32_bf16 v[56:59], v[168:171], v[192:195], v[56:59]
	v_mfma_f32_16x16x32_bf16 v[44:47], v[160:163], v[200:203], v[44:47]
	v_mfma_f32_16x16x32_bf16 v[40:43], v[168:171], v[200:203], v[40:43]
	v_mfma_f32_16x16x32_bf16 v[28:31], v[160:163], v[208:211], v[28:31]
	v_mfma_f32_16x16x32_bf16 v[24:27], v[168:171], v[208:211], v[24:27]
	v_mfma_f32_16x16x32_bf16 v[12:15], v[160:163], v[216:219], v[12:15]
	v_mfma_f32_16x16x32_bf16 v[8:11], v[168:171], v[216:219], v[8:11]
	s_setprio 0
	s_setprio 1
	v_mfma_f32_16x16x32_bf16 v[52:55], v[172:175], v[188:191], v[52:55]
	v_mfma_f32_16x16x32_bf16 v[48:51], v[180:183], v[188:191], v[48:51]
	v_mfma_f32_16x16x32_bf16 v[36:39], v[172:175], v[196:199], v[36:39]
	v_mfma_f32_16x16x32_bf16 v[32:35], v[180:183], v[196:199], v[32:35]
	v_mfma_f32_16x16x32_bf16 v[20:23], v[172:175], v[204:207], v[20:23]
	v_mfma_f32_16x16x32_bf16 v[16:19], v[180:183], v[204:207], v[16:19]
	v_mfma_f32_16x16x32_bf16 v[4:7], v[172:175], v[212:215], v[4:7]
	v_mfma_f32_16x16x32_bf16 v[0:3], v[180:183], v[212:215], v[0:3]
	v_mfma_f32_16x16x32_bf16 v[52:55], v[176:179], v[192:195], v[52:55]
	v_mfma_f32_16x16x32_bf16 v[48:51], v[184:187], v[192:195], v[48:51]
	v_mfma_f32_16x16x32_bf16 v[36:39], v[176:179], v[200:203], v[36:39]
	v_mfma_f32_16x16x32_bf16 v[32:35], v[184:187], v[200:203], v[32:35]
	v_mfma_f32_16x16x32_bf16 v[20:23], v[176:179], v[208:211], v[20:23]
	v_mfma_f32_16x16x32_bf16 v[16:19], v[184:187], v[208:211], v[16:19]
	v_mfma_f32_16x16x32_bf16 v[4:7], v[176:179], v[216:219], v[4:7]
	v_mfma_f32_16x16x32_bf16 v[0:3], v[184:187], v[216:219], v[0:3]
	s_setprio 0
	s_barrier
; #define PG8_STAGE(bufoff, gbase, voff) do { _Pragma("unroll") for (int _i = 0; _i < 2; ++_i) \
;         __builtin_amdgcn_global_load_lds((const unsigned*)((const char*)(gbase) + (voff)[_i]), (LAS unsigned*)(lds + (bufoff) + ldsw + _i * 8192), 16, 0, 0); } while (0)
; #define PG8_LDA(dst, b, h) do { _Pragma("unroll") for (int m = 0; m < 4; ++m) _Pragma("unroll") for (int k = 0; k < 2; ++k) dst[m][k] = *(const LAS bf16x8*)(lds + PG8_SA(b, h) + aoff + m * 2048 + k * 1024); } while (0)
; #define PG8_LDB(dst, b, h) do { _Pragma("unroll") for (int n = 0; n < 2; ++n) _Pragma("unroll") for (int k = 0; k < 2; ++k) dst[n][k] = *(const LAS bf16x8*)(lds + PG8_SB(b, h) + boff + n * 2048 + k * 1024); } while (0)
; #define PG8_MMA(ai, bj, At, Bt) do { __builtin_amdgcn_s_setprio(1); _Pragma("unroll") for (int m = 0; m < 4; ++m) _Pragma("unroll") for (int n = 0; n < 2; ++n) _Pragma("unroll") for (int k = 0; k < 2; ++k) \
;         acc[ai][bj][m][n] = __builtin_amdgcn_mfma_f32_16x16x32_bf16(Bt[n][k], At[m][k], acc[ai][bj][m][n], 0, 0, 0); __builtin_amdgcn_s_setprio(0); } while (0)
; #define PG8_WAIT_V(n) asm volatile("s_waitcnt vmcnt(" #n ")" ::: "memory")
; #define PG8_WAIT_L(n) asm volatile("s_waitcnt lgkmcnt(" #n ")" ::: "memory")
; #define PG8_BAR __builtin_amdgcn_s_barrier()
; #define PG8_SCHED __builtin_amdgcn_sched_barrier(0)
; template <class Epi, class Sched>
; __device__ __forceinline__ void gemm_phase(LAS unsigned char* lds, const Gemm g, const Sched& S, const Epi& E) {
;     ...
;             PG8_LDB(B0, 1, 0); PG8_LDB(B1, 1, 1); PG8_SCHED; PG8_LDA(At, 1, 0); PG8_STAGE(PG8_SA(0, 1), a2 + hstepA, voffA);
;             PG8_WAIT_V(8); PG8_WAIT_L(0); PG8_BAR; PG8_MMA(0, 0, At, B0); PG8_MMA(0, 1, At, B1); PG8_BAR; PG8_SCHED;
	s_add_i32 s48, 0, 0x18000
	v_add_u32_e32 v159, s48, v153
	s_add_i32 s49, 0, 0x1c000
	ds_read_b128 v[146:149], v159
	ds_read_b128 v[160:163], v159 offset:1024
	ds_read_b128 v[164:167], v159 offset:2048
	ds_read_b128 v[168:171], v159 offset:3072
	v_add_u32_e32 v159, s49, v153
	ds_read_b128 v[172:175], v159
	ds_read_b128 v[176:179], v159 offset:1024
	ds_read_b128 v[180:183], v159 offset:2048
	ds_read_b128 v[184:187], v159 offset:3072
	s_add_u32 s40, s40, 0x80000
	s_addc_u32 s41, s41, 0
	s_mov_b32 m0, s34
	v_lshl_add_u64 v[226:227], s[40:41], 0, v[128:129]
	ds_read_b128 v[188:191], v157 offset:32768
	ds_read_b128 v[192:195], v157 offset:33792
	ds_read_b128 v[196:199], v157 offset:34816
	ds_read_b128 v[200:203], v157 offset:35840
	ds_read_b128 v[204:207], v157 offset:36864
	ds_read_b128 v[208:211], v157 offset:37888
	ds_read_b128 v[212:215], v157 offset:38912
	ds_read_b128 v[216:219], v157 offset:39936
	global_load_lds_dwordx4 v[226:227], off
	v_lshl_add_u64 v[226:227], s[40:41], 0, v[132:133]
	s_mov_b32 m0, s35
	s_nop 0
	global_load_lds_dwordx4 v[226:227], off
	s_waitcnt vmcnt(8)
	s_waitcnt lgkmcnt(0)
	s_barrier
	s_setprio 1
	s_waitcnt lgkmcnt(0)
	v_mfma_f32_16x16x32_bf16 v[124:127], v[146:149], v[188:191], v[124:127]
	v_mfma_f32_16x16x32_bf16 v[120:123], v[164:167], v[188:191], v[120:123]
	v_mfma_f32_16x16x32_bf16 v[108:111], v[146:149], v[196:199], v[108:111]
	v_mfma_f32_16x16x32_bf16 v[104:107], v[164:167], v[196:199], v[104:107]
	v_mfma_f32_16x16x32_bf16 v[92:95], v[146:149], v[204:207], v[92:95]
	v_mfma_f32_16x16x32_bf16 v[88:91], v[164:167], v[204:207], v[88:91]
	v_mfma_f32_16x16x32_bf16 v[76:79], v[146:149], v[212:215], v[76:79]
	v_mfma_f32_16x16x32_bf16 v[72:75], v[164:167], v[212:215], v[72:75]
	v_mfma_f32_16x16x32_bf16 v[124:127], v[160:163], v[192:195], v[124:127]
	v_mfma_f32_16x16x32_bf16 v[120:123], v[168:171], v[192:195], v[120:123]
	v_mfma_f32_16x16x32_bf16 v[108:111], v[160:163], v[200:203], v[108:111]
	v_mfma_f32_16x16x32_bf16 v[104:107], v[168:171], v[200:203], v[104:107]
	v_mfma_f32_16x16x32_bf16 v[92:95], v[160:163], v[208:211], v[92:95]
	v_mfma_f32_16x16x32_bf16 v[88:91], v[168:171], v[208:211], v[88:91]
	v_mfma_f32_16x16x32_bf16 v[76:79], v[160:163], v[216:219], v[76:79]
	v_mfma_f32_16x16x32_bf16 v[72:75], v[168:171], v[216:219], v[72:75]
	s_setprio 0
	s_setprio 1
	v_mfma_f32_16x16x32_bf16 v[116:119], v[172:175], v[188:191], v[116:119]
	v_mfma_f32_16x16x32_bf16 v[112:115], v[180:183], v[188:191], v[112:115]
	v_mfma_f32_16x16x32_bf16 v[100:103], v[172:175], v[196:199], v[100:103]
	v_mfma_f32_16x16x32_bf16 v[96:99], v[180:183], v[196:199], v[96:99]
	v_mfma_f32_16x16x32_bf16 v[84:87], v[172:175], v[204:207], v[84:87]
	v_mfma_f32_16x16x32_bf16 v[80:83], v[180:183], v[204:207], v[80:83]
	v_mfma_f32_16x16x32_bf16 v[68:71], v[172:175], v[212:215], v[68:71]
	v_mfma_f32_16x16x32_bf16 v[64:67], v[180:183], v[212:215], v[64:67]
	v_mfma_f32_16x16x32_bf16 v[116:119], v[176:179], v[192:195], v[116:119]
	v_mfma_f32_16x16x32_bf16 v[112:115], v[184:187], v[192:195], v[112:115]
	v_mfma_f32_16x16x32_bf16 v[100:103], v[176:179], v[200:203], v[100:103]
	v_mfma_f32_16x16x32_bf16 v[96:99], v[184:187], v[200:203], v[96:99]
	v_mfma_f32_16x16x32_bf16 v[84:87], v[176:179], v[208:211], v[84:87]
	v_mfma_f32_16x16x32_bf16 v[80:83], v[184:187], v[208:211], v[80:83]
	v_mfma_f32_16x16x32_bf16 v[68:71], v[176:179], v[216:219], v[68:71]
	v_mfma_f32_16x16x32_bf16 v[64:67], v[184:187], v[216:219], v[64:67]
	s_setprio 0
	s_barrier
; #define PG8_STAGE(bufoff, gbase, voff) do { _Pragma("unroll") for (int _i = 0; _i < 2; ++_i) \
;         __builtin_amdgcn_global_load_lds((const unsigned*)((const char*)(gbase) + (voff)[_i]), (LAS unsigned*)(lds + (bufoff) + ldsw + _i * 8192), 16, 0, 0); } while (0)
; #define PG8_LDA(dst, b, h) do { _Pragma("unroll") for (int m = 0; m < 4; ++m) _Pragma("unroll") for (int k = 0; k < 2; ++k) dst[m][k] = *(const LAS bf16x8*)(lds + PG8_SA(b, h) + aoff + m * 2048 + k * 1024); } while (0)
; #define PG8_MMA(ai, bj, At, Bt) do { __builtin_amdgcn_s_setprio(1); _Pragma("unroll") for (int m = 0; m < 4; ++m) _Pragma("unroll") for (int n = 0; n < 2; ++n) _Pragma("unroll") for (int k = 0; k < 2; ++k) \
;         acc[ai][bj][m][n] = __builtin_amdgcn_mfma_f32_16x16x32_bf16(Bt[n][k], At[m][k], acc[ai][bj][m][n], 0, 0, 0); __builtin_amdgcn_s_setprio(0); } while (0)
; #define PG8_WAIT_V(n) asm volatile("s_waitcnt vmcnt(" #n ")" ::: "memory")
; #define PG8_WAIT_L(n) asm volatile("s_waitcnt lgkmcnt(" #n ")" ::: "memory")
; #define PG8_BAR __builtin_amdgcn_s_barrier()
; #define PG8_SCHED __builtin_amdgcn_sched_barrier(0)
; template <class Epi, class Sched>
; __device__ __forceinline__ void gemm_phase(LAS unsigned char* lds, const Gemm g, const Sched& S, const Epi& E) {
;     ...
;             PG8_LDA(At, 1, 1); PG8_STAGE(PG8_SB(1, 0), b3, voffB); PG8_STAGE(PG8_SB(1, 1), b3 + hstepB, voffB); PG8_STAGE(PG8_SA(1, 0), a3, voffA);
;             PG8_WAIT_V(8); PG8_WAIT_L(0); PG8_BAR; PG8_MMA(1, 0, At, B0); PG8_MMA(1, 1, At, B1); PG8_BAR; PG8_SCHED;
;         }
	s_add_i32 s40, s48, s5
	v_lshl_add_u64 v[150:151], v[150:151], 0, s[10:11]
	s_mov_b32 m0, s40
	ds_read_b128 v[188:191], v157 offset:49152
	ds_read_b128 v[192:195], v157 offset:50176
	ds_read_b128 v[196:199], v157 offset:51200
	ds_read_b128 v[200:203], v157 offset:52224
	ds_read_b128 v[204:207], v157 offset:53248
	ds_read_b128 v[208:211], v157 offset:54272
	ds_read_b128 v[212:215], v157 offset:55296
	ds_read_b128 v[216:219], v157 offset:56320
	global_load_lds_dwordx4 v[150:151], off
	s_add_i32 m0, s40, 0x2000
	s_add_u32 s38, s38, 0x80080
	v_lshl_add_u64 v[150:151], v[220:221], 0, s[10:11]
	s_addc_u32 s39, s39, 0
	s_add_i32 s40, s49, s5
	global_load_lds_dwordx4 v[150:151], off
	v_lshl_add_u64 v[150:151], s[38:39], 0, v[130:131]
	s_mov_b32 m0, s40
	s_nop 0
	global_load_lds_dwordx4 v[150:151], off
	v_lshl_add_u64 v[150:151], s[38:39], 0, v[134:135]
	s_add_i32 m0, s40, 0x2000
	s_nop 0
	global_load_lds_dwordx4 v[150:151], off
	v_lshl_add_u64 v[150:151], v[222:223], 0, s[98:99]
	s_mov_b32 m0, s43
	s_nop 0
	global_load_lds_dwordx4 v[150:151], off
	v_lshl_add_u64 v[150:151], v[224:225], 0, s[98:99]
	s_mov_b32 m0, s44
	s_nop 0
	global_load_lds_dwordx4 v[150:151], off
	s_waitcnt vmcnt(8)
	s_waitcnt lgkmcnt(0)
	s_barrier
	s_setprio 1
	s_waitcnt lgkmcnt(0)
	v_mfma_f32_16x16x32_bf16 v[60:63], v[146:149], v[188:191], v[60:63]
	v_mfma_f32_16x16x32_bf16 v[56:59], v[164:167], v[188:191], v[56:59]
	v_mfma_f32_16x16x32_bf16 v[44:47], v[146:149], v[196:199], v[44:47]
	v_mfma_f32_16x16x32_bf16 v[40:43], v[164:167], v[196:199], v[40:43]
	v_mfma_f32_16x16x32_bf16 v[28:31], v[146:149], v[204:207], v[28:31]
	v_mfma_f32_16x16x32_bf16 v[24:27], v[164:167], v[204:207], v[24:27]
	v_mfma_f32_16x16x32_bf16 v[12:15], v[146:149], v[212:215], v[12:15]
	v_mfma_f32_16x16x32_bf16 v[8:11], v[164:167], v[212:215], v[8:11]
	v_mfma_f32_16x16x32_bf16 v[60:63], v[160:163], v[192:195], v[60:63]
	v_mfma_f32_16x16x32_bf16 v[56:59], v[168:171], v[192:195], v[56:59]
	v_mfma_f32_16x16x32_bf16 v[44:47], v[160:163], v[200:203], v[44:47]
	v_mfma_f32_16x16x32_bf16 v[40:43], v[168:171], v[200:203], v[40:43]
	v_mfma_f32_16x16x32_bf16 v[28:31], v[160:163], v[208:211], v[28:31]
	v_mfma_f32_16x16x32_bf16 v[24:27], v[168:171], v[208:211], v[24:27]
	v_mfma_f32_16x16x32_bf16 v[12:15], v[160:163], v[216:219], v[12:15]
	v_mfma_f32_16x16x32_bf16 v[8:11], v[168:171], v[216:219], v[8:11]
	s_setprio 0
	s_setprio 1
	v_mfma_f32_16x16x32_bf16 v[52:55], v[172:175], v[188:191], v[52:55]
	v_mfma_f32_16x16x32_bf16 v[48:51], v[180:183], v[188:191], v[48:51]
	v_mfma_f32_16x16x32_bf16 v[36:39], v[172:175], v[196:199], v[36:39]
	v_mfma_f32_16x16x32_bf16 v[32:35], v[180:183], v[196:199], v[32:35]
	v_mfma_f32_16x16x32_bf16 v[20:23], v[172:175], v[204:207], v[20:23]
	v_mfma_f32_16x16x32_bf16 v[16:19], v[180:183], v[204:207], v[16:19]
	v_mfma_f32_16x16x32_bf16 v[4:7], v[172:175], v[212:215], v[4:7]
	v_mfma_f32_16x16x32_bf16 v[0:3], v[180:183], v[212:215], v[0:3]
	v_mfma_f32_16x16x32_bf16 v[52:55], v[176:179], v[192:195], v[52:55]
	v_mfma_f32_16x16x32_bf16 v[48:51], v[184:187], v[192:195], v[48:51]
	v_mfma_f32_16x16x32_bf16 v[36:39], v[176:179], v[200:203], v[36:39]
	v_mfma_f32_16x16x32_bf16 v[32:35], v[184:187], v[200:203], v[32:35]
	v_mfma_f32_16x16x32_bf16 v[20:23], v[176:179], v[208:211], v[20:23]
	v_mfma_f32_16x16x32_bf16 v[16:19], v[184:187], v[208:211], v[16:19]
	v_mfma_f32_16x16x32_bf16 v[4:7], v[176:179], v[216:219], v[4:7]
	v_mfma_f32_16x16x32_bf16 v[0:3], v[184:187], v[216:219], v[0:3]
	s_setprio 0
	s_barrier
	s_add_i32 s55, s55, 2
	s_add_u32 s36, s36, 0x1000
	s_addc_u32 s37, s37, 0
	s_add_u32 s53, s53, 0x100
	s_addc_u32 s54, s54, 0
	s_cmp_gt_u32 s55, 29
	s_cbranch_scc0 .LBB0_837
	s_and_b64 vcc, exec, s[12:13]
	s_cbranch_vccz .LBB0_840
	s_barrier

; __device__ __forceinline__ void unpack8(const u32x4 w, f32x4& a, f32x4& b) { a = (f32x4){bf_lo(w.x), bf_hi(w.x), bf_lo(w.y), bf_hi(w.y)}; b = (f32x4){bf_lo(w.z), bf_hi(w.z), bf_lo(w.w), bf_hi(w.w)}; }
;     __device__ __forceinline__ void operator()(AccRef acc, const Unit& u, int wr, int wc, int fr, int fq) const {
;     ...
;         const int lane = fr + 16 * fq, rowb = u.pm * 256 + wr * 64 + fr, colb = u.pn * 256 + wc * 32 + 8 * fq;
; #pragma unroll
;         for (int ai = 0; ai < 2; ++ai) { u32x4 xw[4][2];
; #pragma unroll
;             for (int m = 0; m < 4; ++m)
; #pragma unroll
;                 for (int bj = 0; bj < 2; ++bj) xw[m][bj] = *(const u32x4*)(X1B + (size_t)(rowb + ai * 128 + m * 16) * D + colb + bj * 128);
; #pragma unroll
;             for (int m = 0; m < 4; ++m) { float sq = 0.f;
; #pragma unroll
;                 for (int bj = 0; bj < 2; ++bj) { f32x4 x0, x1; unpack8(xw[m][bj], x0, x1); const f32x4 a0 = acc[ai][bj][m][0] + x0, a1 = acc[ai][bj][m][1] + x1;
;                     sq += (a0[0] * a0[0] + a0[1] * a0[1]) + (a0[2] * a0[2] + a0[3] * a0[3]) + (a1[0] * a1[0] + a1[1] * a1[1]) + (a1[2] * a1[2] + a1[3] * a1[3]); }
;                 sq += __shfl_xor(sq, 16); sq += __shfl_xor(sq, 32);
;                 if (fq == 0) atomicAdd(ssq3 + rowb + ai * 128 + m * 16, sq); }
.LBB0_923:
	v_lshl_add_u32 v202, s18, 8, v164
	v_lshl_or_b32 v204, s16, 8, v165
	v_ashrrev_i32_e32 v205, 31, v204
	v_ashrrev_i32_e32 v203, 31, v202
	v_lshrrev_b32_e32 v182, 5, v204
	v_lshlrev_b32_e32 v182, 10, v182
	v_and_b32_e32 v183, 63, v211
	v_lshl_add_u32 v182, v183, 4, v182
	v_and_b32_e32 v183, 15, v211
	v_lshlrev_b32_e32 v183, 12, v183
	v_sub_u32_e32 v182, v182, v183
	v_add_u32_e32 v182, 0x1000, v182
	v_ashrrev_i32_e32 v183, 31, v182
	v_lshl_add_u64 v[182:183], v[182:183], 0, s[14:15]
	v_lshlrev_b64 v[128:129], 12, v[202:203]
	v_lshl_add_u64 v[206:207], v[182:183], 0, v[128:129]
	global_load_dwordx4 v[176:179], v[206:207], off offset:-4096
	global_load_dwordx4 v[196:199], v[206:207], off
	v_or_b32_e32 v192, 16, v202
	v_or_b32_e32 v180, 32, v202
	v_or_b32_e32 v174, 48, v202
	v_ashrrev_i32_e32 v193, 31, v192
	v_ashrrev_i32_e32 v181, 31, v180
	v_ashrrev_i32_e32 v175, 31, v174
	v_lshlrev_b64 v[128:129], 12, v[192:193]
	v_lshlrev_b64 v[130:131], 12, v[180:181]
	v_lshlrev_b64 v[132:133], 12, v[174:175]
	v_lshl_add_u64 v[194:195], v[182:183], 0, v[128:129]
	v_lshl_add_u64 v[188:189], v[182:183], 0, v[130:131]
	v_lshl_add_u64 v[184:185], v[182:183], 0, v[132:133]
	global_load_dwordx4 v[148:151], v[194:195], off offset:-4096
	global_load_dwordx4 v[144:147], v[194:195], off
	global_load_dwordx4 v[140:143], v[188:189], off offset:-4096
	global_load_dwordx4 v[136:139], v[188:189], off
	global_load_dwordx4 v[132:135], v[184:185], off offset:-4096
	global_load_dwordx4 v[128:131], v[184:185], off
	v_and_b32_e32 v173, 64, v211
	v_xor_b32_e32 v172, 16, v211
	v_add_u32_e32 v213, 64, v173
	v_cmp_lt_i32_e32 vcc, v172, v213
	s_waitcnt vmcnt(0)
	v_and_b32_e32 v173, 0xffff0000, v176
	v_cndmask_b32_e32 v172, v211, v172, vcc
	v_lshlrev_b32_e32 v212, 2, v172
	v_lshlrev_b32_e32 v172, 16, v176
	v_lshlrev_b32_e32 v176, 16, v177
	v_and_b32_e32 v177, 0xffff0000, v177
	v_lshlrev_b32_e32 v190, 16, v196
	v_and_b32_e32 v191, 0xffff0000, v196
	v_lshlrev_b32_e32 v196, 16, v197
	v_and_b32_e32 v197, 0xffff0000, v197
	v_lshlrev_b32_e32 v186, 16, v178
	v_and_b32_e32 v187, 0xffff0000, v178
	v_lshlrev_b32_e32 v200, 16, v198
	v_and_b32_e32 v201, 0xffff0000, v198
	v_pk_add_f32 v[176:177], v[126:127], v[176:177]
	v_pk_add_f32 v[172:173], v[124:125], v[172:173]
	v_pk_add_f32 v[196:197], v[110:111], v[196:197]
	v_pk_add_f32 v[190:191], v[108:109], v[190:191]
	v_lshlrev_b32_e32 v178, 16, v179
	v_and_b32_e32 v179, 0xffff0000, v179
	v_lshlrev_b32_e32 v198, 16, v199
	v_and_b32_e32 v199, 0xffff0000, v199
	v_pk_add_f32 v[186:187], v[120:121], v[186:187]
	v_pk_add_f32 v[200:201], v[100:101], v[200:201]
	v_mul_f32_e32 v173, v173, v173
	v_mul_f32_e32 v177, v177, v177
	v_mul_f32_e32 v191, v191, v191
	v_mul_f32_e32 v197, v197, v197
	v_pk_add_f32 v[178:179], v[122:123], v[178:179]
	v_pk_add_f32 v[198:199], v[102:103], v[198:199]
	v_mul_f32_e32 v187, v187, v187
	v_mul_f32_e32 v201, v201, v201
	v_fmac_f32_e32 v173, v172, v172
	v_fmac_f32_e32 v177, v176, v176
	v_fmac_f32_e32 v191, v190, v190
	v_fmac_f32_e32 v197, v196, v196
	v_mul_f32_e32 v179, v179, v179
	v_mul_f32_e32 v199, v199, v199
	v_fmac_f32_e32 v187, v186, v186
	v_fmac_f32_e32 v201, v200, v200
	v_add_f32_e32 v172, v173, v177
	v_add_f32_e32 v173, v191, v197
	v_fmac_f32_e32 v179, v178, v178
	v_fmac_f32_e32 v199, v198, v198
	v_add_f32_e32 v172, v187, v172
	v_add_f32_e32 v173, v201, v173
	v_add_f32_e32 v172, v179, v172
	v_add_f32_e32 v173, v199, v173
	v_add_f32_e32 v172, v172, v173
	ds_bpermute_b32 v173, v212, v172
	v_xor_b32_e32 v176, 32, v211
	v_cmp_lt_i32_e32 vcc, v176, v213
	s_nop 1
	v_cndmask_b32_e32 v176, v211, v176, vcc
	v_lshlrev_b32_e32 v213, 2, v176
	s_waitcnt lgkmcnt(0)
	v_add_f32_e32 v176, v172, v173
	ds_bpermute_b32 v177, v213, v176
	v_lshl_add_u64 v[172:173], v[202:203], 2, s[22:23]
	s_and_saveexec_b64 s[8:9], s[0:1]
	s_cbranch_execz .LBB0_925
	s_waitcnt lgkmcnt(0)
	v_add_f32_e32 v176, v176, v177
	global_atomic_add_f32 v[172:173], v176, off

; __device__ __forceinline__ void unpack8(const u32x4 w, f32x4& a, f32x4& b) { a = (f32x4){bf_lo(w.x), bf_hi(w.x), bf_lo(w.y), bf_hi(w.y)}; b = (f32x4){bf_lo(w.z), bf_hi(w.z), bf_lo(w.w), bf_hi(w.w)}; }
;     __device__ __forceinline__ void operator()(AccRef acc, const Unit& u, int wr, int wc, int fr, int fq) const {
;     ...
;         for (int ai = 0; ai < 2; ++ai) { u32x4 xw[4][2];
; #pragma unroll
;             for (int m = 0; m < 4; ++m)
; #pragma unroll
;                 for (int bj = 0; bj < 2; ++bj) xw[m][bj] = *(const u32x4*)(X1B + (size_t)(rowb + ai * 128 + m * 16) * D + colb + bj * 128);
; #pragma unroll
;             for (int m = 0; m < 4; ++m) { float sq = 0.f;
; #pragma unroll
;                 for (int bj = 0; bj < 2; ++bj) { f32x4 x0, x1; unpack8(xw[m][bj], x0, x1); const f32x4 a0 = acc[ai][bj][m][0] + x0, a1 = acc[ai][bj][m][1] + x1;
;                     sq += (a0[0] * a0[0] + a0[1] * a0[1]) + (a0[2] * a0[2] + a0[3] * a0[3]) + (a1[0] * a1[0] + a1[1] * a1[1]) + (a1[2] * a1[2] + a1[3] * a1[3]); }
;                 sq += __shfl_xor(sq, 16); sq += __shfl_xor(sq, 32);
;                 if (fq == 0) atomicAdd(ssq3 + rowb + ai * 128 + m * 16, sq); }
.LBB0_931:
	s_or_b64 exec, exec, s[8:9]
	v_add_u32_e32 v196, 0x80, v202
	v_ashrrev_i32_e32 v197, 31, v196
	s_waitcnt lgkmcnt(0)
	v_lshlrev_b64 v[128:129], 12, v[196:197]
	v_lshl_add_u64 v[198:199], v[182:183], 0, v[128:129]
	global_load_dwordx4 v[214:217], v[198:199], off offset:-4096
	global_load_dwordx4 v[218:221], v[198:199], off
	v_add_u32_e32 v190, 0x90, v202
	v_add_u32_e32 v178, 0xa0, v202
	v_add_u32_e32 v176, 0xb0, v202
	v_ashrrev_i32_e32 v191, 31, v190
	v_ashrrev_i32_e32 v179, 31, v178
	v_ashrrev_i32_e32 v177, 31, v176
	v_lshlrev_b64 v[128:129], 12, v[190:191]
	v_lshlrev_b64 v[130:131], 12, v[178:179]
	v_lshlrev_b64 v[132:133], 12, v[176:177]
	v_lshl_add_u64 v[200:201], v[182:183], 0, v[128:129]
	v_lshl_add_u64 v[186:187], v[182:183], 0, v[130:131]
	v_lshl_add_u64 v[182:183], v[182:183], 0, v[132:133]
	global_load_dwordx4 v[148:151], v[200:201], off offset:-4096
	global_load_dwordx4 v[144:147], v[200:201], off
	global_load_dwordx4 v[140:143], v[186:187], off offset:-4096
	global_load_dwordx4 v[136:139], v[186:187], off
	global_load_dwordx4 v[132:135], v[182:183], off offset:-4096
	global_load_dwordx4 v[128:131], v[182:183], off
	s_waitcnt vmcnt(7)
	v_lshlrev_b32_e32 v222, 16, v214
	v_and_b32_e32 v223, 0xffff0000, v214
	v_lshlrev_b32_e32 v214, 16, v215
	v_and_b32_e32 v215, 0xffff0000, v215
	s_waitcnt vmcnt(6)
	v_lshlrev_b32_e32 v226, 16, v218
	v_and_b32_e32 v227, 0xffff0000, v218
	v_lshlrev_b32_e32 v218, 16, v219
	v_and_b32_e32 v219, 0xffff0000, v219
	v_lshlrev_b32_e32 v224, 16, v216
	v_and_b32_e32 v225, 0xffff0000, v216
	v_lshlrev_b32_e32 v228, 16, v220
	v_and_b32_e32 v229, 0xffff0000, v220
	v_pk_add_f32 v[214:215], v[62:63], v[214:215]
	v_pk_add_f32 v[222:223], v[60:61], v[222:223]
	v_pk_add_f32 v[218:219], v[46:47], v[218:219]
	v_pk_add_f32 v[226:227], v[44:45], v[226:227]
	v_lshlrev_b32_e32 v216, 16, v217
	v_and_b32_e32 v217, 0xffff0000, v217
	v_lshlrev_b32_e32 v220, 16, v221
	v_and_b32_e32 v221, 0xffff0000, v221
	v_pk_add_f32 v[224:225], v[56:57], v[224:225]
	v_pk_add_f32 v[228:229], v[36:37], v[228:229]
	v_mul_f32_e32 v223, v223, v223
	v_mul_f32_e32 v215, v215, v215
	v_mul_f32_e32 v227, v227, v227
	v_mul_f32_e32 v219, v219, v219
	v_pk_add_f32 v[216:217], v[58:59], v[216:217]
	v_pk_add_f32 v[220:221], v[38:39], v[220:221]
	v_mul_f32_e32 v225, v225, v225
	v_mul_f32_e32 v229, v229, v229
	v_fmac_f32_e32 v223, v222, v222
	v_fmac_f32_e32 v215, v214, v214
	v_fmac_f32_e32 v227, v226, v226
	v_fmac_f32_e32 v219, v218, v218
	v_mul_f32_e32 v217, v217, v217
	v_mul_f32_e32 v221, v221, v221
	v_fmac_f32_e32 v225, v224, v224
	v_fmac_f32_e32 v229, v228, v228
	v_add_f32_e32 v214, v223, v215
	v_add_f32_e32 v215, v227, v219
	v_fmac_f32_e32 v217, v216, v216
	v_fmac_f32_e32 v221, v220, v220
	v_add_f32_e32 v214, v225, v214
	v_add_f32_e32 v215, v229, v215
	v_add_f32_e32 v214, v217, v214
	v_add_f32_e32 v215, v221, v215
	v_add_f32_e32 v214, v214, v215
	ds_bpermute_b32 v215, v212, v214
	s_waitcnt lgkmcnt(0)
	v_add_f32_e32 v214, v214, v215
	ds_bpermute_b32 v215, v213, v214
	s_and_saveexec_b64 s[8:9], s[0:1]
	s_cbranch_execz .LBB0_933
	s_waitcnt lgkmcnt(0)
	v_add_f32_e32 v214, v214, v215
	global_atomic_add_f32 v[172:173], v214, off offset:512

; __device__ __forceinline__ void unpack8(const u32x4 w, f32x4& a, f32x4& b) { a = (f32x4){bf_lo(w.x), bf_hi(w.x), bf_lo(w.y), bf_hi(w.y)}; b = (f32x4){bf_lo(w.z), bf_hi(w.z), bf_lo(w.w), bf_hi(w.w)}; }
;     __device__ __forceinline__ void operator()(AccRef acc, const Unit& u, int wr, int wc, int fr, int fq) const {
;     ...
;         f32x4 gv[2][2];
; #pragma unroll
;         for (int bj = 0; bj < 2; ++bj) { gv[bj][0] = *(const f32x4*)(g3 + colb + bj * 128); gv[bj][1] = *(const f32x4*)(g3 + colb + bj * 128 + 4); }
; #pragma unroll
;         for (int am = 0; am < 4; ++am) { const int ai = am >> 1, m0 = (am & 1) * 2; u32x4 xw[2][2]; float rs[2];
; #pragma unroll
;             for (int mm = 0; mm < 2; ++mm) { rs[mm] = __hip_atomic_load(ssq3 + rowb + ai * 128 + (m0 + mm) * 16, __ATOMIC_RELAXED, __HIP_MEMORY_SCOPE_AGENT);
; #pragma unroll
;                 for (int bj = 0; bj < 2; ++bj) xw[mm][bj] = *(const u32x4*)(X1B + (size_t)(rowb + ai * 128 + (m0 + mm) * 16) * D + colb + bj * 128); }
; #pragma unroll
;             for (int mm = 0; mm < 2; ++mm) { const int m = m0 + mm; const float r3 = rsqrtf(rs[mm] * (1.0f / D) + EPS); float* orow = out + (size_t)(rowb + ai * 128 + m * 16) * D + colb;
; #pragma unroll
;                 for (int bj = 0; bj < 2; ++bj) { f32x4 x0, x1; unpack8(xw[mm][bj], x0, x1);
;                     *(f32x4*)(orow + bj * 128) = (acc[ai][bj][m][0] + x0) * r3 * gv[bj][0]; *(f32x4*)(orow + bj * 128 + 4) = (acc[ai][bj][m][1] + x1) * r3 * gv[bj][1]; } }
;             asm volatile("" ::: "memory"); }
.LBB0_948:
	v_lshlrev_b64 v[144:145], 2, v[204:205]
	v_lshl_add_u64 v[132:133], s[26:27], 0, v[144:145]
	global_load_dwordx4 v[136:139], v[132:133], off offset:16
	global_load_dwordx4 v[140:143], v[132:133], off
	s_waitcnt lgkmcnt(0)
	global_load_dwordx4 v[128:131], v[132:133], off offset:528
	s_nop 0
	global_load_dwordx4 v[132:135], v[132:133], off offset:512
	s_nop 0
	global_load_dword v217, v[172:173], off sc1
	global_load_dwordx4 v[148:151], v[206:207], off offset:-4096
	s_nop 0
	global_load_dwordx4 v[204:207], v[206:207], off
	s_nop 0
	global_load_dword v216, v[172:173], off offset:64 sc1
	global_load_dwordx4 v[212:215], v[194:195], off offset:-4096
	v_lshlrev_b64 v[192:193], 13, v[192:193]
	v_lshl_add_u64 v[218:219], s[28:29], 0, v[192:193]
	global_load_dwordx4 v[192:195], v[194:195], off
	s_mov_b32 s8, 0x358637bd
	v_mov_b64_e32 v[146:147], s[8:9]
	v_lshlrev_b64 v[202:203], 13, v[202:203]
	v_lshl_add_u64 v[202:203], s[28:29], 0, v[202:203]
	v_lshl_add_u64 v[224:225], v[202:203], 0, v[144:145]
	v_lshl_add_u64 v[226:227], v[218:219], 0, v[144:145]
	v_lshlrev_b64 v[180:181], 13, v[180:181]
	v_lshl_add_u64 v[180:181], s[28:29], 0, v[180:181]
	v_lshl_add_u64 v[180:181], v[180:181], 0, v[144:145]
	v_lshlrev_b64 v[178:179], 13, v[178:179]
	v_lshl_add_u64 v[178:179], s[28:29], 0, v[178:179]
	s_waitcnt vmcnt(4)
	v_lshlrev_b32_e32 v202, 16, v148
	v_and_b32_e32 v203, 0xffff0000, v148
	s_waitcnt vmcnt(2)
	v_pk_fma_f32 v[216:217], v[216:217], s[38:39], v[146:147] op_sel_hi:[1,0,0]
	v_lshlrev_b32_e32 v148, 16, v149
	v_mul_f32_e32 v232, 0x4b800000, v217
	v_cmp_gt_f32_e32 vcc, s83, v217
	v_mul_f32_e32 v233, 0x4b800000, v216
	v_cmp_gt_f32_e64 s[8:9], s83, v216
	v_cndmask_b32_e32 v217, v217, v232, vcc
	v_rsq_f32_e32 v217, v217
	v_cndmask_b32_e64 v216, v216, v233, s[8:9]
	v_rsq_f32_e32 v234, v216
	v_and_b32_e32 v149, 0xffff0000, v149
	s_waitcnt vmcnt(1)
	v_lshlrev_b32_e32 v230, 16, v214
	v_and_b32_e32 v231, 0xffff0000, v214
	v_lshlrev_b32_e32 v214, 16, v215
	v_and_b32_e32 v215, 0xffff0000, v215
	v_mul_f32_e32 v216, 0x45800000, v217
	v_lshlrev_b32_e32 v218, 16, v150
	v_and_b32_e32 v219, 0xffff0000, v150
	v_lshlrev_b32_e32 v150, 16, v151
	v_and_b32_e32 v151, 0xffff0000, v151
	v_lshlrev_b32_e32 v220, 16, v204
	v_and_b32_e32 v221, 0xffff0000, v204
	v_lshlrev_b32_e32 v204, 16, v205
	v_and_b32_e32 v205, 0xffff0000, v205
	v_lshlrev_b32_e32 v222, 16, v206
	v_and_b32_e32 v223, 0xffff0000, v206
	v_lshlrev_b32_e32 v206, 16, v207
	v_and_b32_e32 v207, 0xffff0000, v207
	v_lshlrev_b32_e32 v228, 16, v212
	v_and_b32_e32 v229, 0xffff0000, v212
	v_lshlrev_b32_e32 v212, 16, v213
	v_and_b32_e32 v213, 0xffff0000, v213
	v_pk_add_f32 v[148:149], v[126:127], v[148:149]
	v_pk_add_f32 v[202:203], v[124:125], v[202:203]
	v_pk_add_f32 v[232:233], v[114:115], v[214:215]
	v_pk_add_f32 v[214:215], v[112:113], v[230:231]
	v_mul_f32_e32 v230, 0x45800000, v234
	v_cndmask_b32_e32 v216, v217, v216, vcc
	v_pk_add_f32 v[150:151], v[122:123], v[150:151]
	v_pk_add_f32 v[218:219], v[120:121], v[218:219]
	v_pk_add_f32 v[204:205], v[110:111], v[204:205]
	v_pk_add_f32 v[220:221], v[108:109], v[220:221]
	v_pk_add_f32 v[206:207], v[102:103], v[206:207]
	v_pk_add_f32 v[222:223], v[100:101], v[222:223]
	v_pk_add_f32 v[212:213], v[118:119], v[212:213]
	v_pk_add_f32 v[228:229], v[116:117], v[228:229]
	v_cndmask_b32_e64 v230, v234, v230, s[8:9]
	v_pk_mul_f32 v[202:203], v[202:203], v[216:217] op_sel_hi:[1,0]
	v_pk_mul_f32 v[148:149], v[148:149], v[216:217] op_sel_hi:[1,0]
	v_pk_mul_f32 v[218:219], v[218:219], v[216:217] op_sel_hi:[1,0]
	v_pk_mul_f32 v[234:235], v[150:151], v[216:217] op_sel_hi:[1,0]
	v_pk_mul_f32 v[220:221], v[216:217], v[220:221] op_sel_hi:[0,1]
	v_pk_mul_f32 v[236:237], v[216:217], v[204:205] op_sel_hi:[0,1]
	v_pk_mul_f32 v[222:223], v[216:217], v[222:223] op_sel_hi:[0,1]
	v_pk_mul_f32 v[206:207], v[216:217], v[206:207] op_sel_hi:[0,1]
	v_pk_mul_f32 v[228:229], v[228:229], v[230:231] op_sel_hi:[1,0]
	v_pk_mul_f32 v[238:239], v[212:213], v[230:231] op_sel_hi:[1,0]
	v_pk_mul_f32 v[150:151], v[142:143], v[148:149]
	v_pk_mul_f32 v[148:149], v[140:141], v[202:203]
	v_pk_mul_f32 v[240:241], v[214:215], v[230:231] op_sel_hi:[1,0]
	v_pk_mul_f32 v[204:205], v[138:139], v[234:235]
	v_pk_mul_f32 v[202:203], v[136:137], v[218:219]
	v_pk_mul_f32 v[214:215], v[134:135], v[236:237]
	v_pk_mul_f32 v[212:213], v[132:133], v[220:221]
	v_pk_mul_f32 v[218:219], v[130:131], v[206:207]
	v_pk_mul_f32 v[216:217], v[128:129], v[222:223]
	v_pk_mul_f32 v[222:223], v[142:143], v[238:239]
	v_pk_mul_f32 v[220:221], v[140:141], v[228:229]
	global_store_dwordx4 v[224:225], v[148:151], off
	global_store_dwordx4 v[224:225], v[202:205], off offset:16
	global_store_dwordx4 v[224:225], v[212:215], off offset:512
	global_store_dwordx4 v[224:225], v[216:219], off offset:528
	global_store_dwordx4 v[226:227], v[220:223], off
	v_pk_mul_f32 v[148:149], v[232:233], v[230:231] op_sel_hi:[1,0]
	s_nop 0
	v_pk_mul_f32 v[150:151], v[138:139], v[148:149]
	v_pk_mul_f32 v[148:149], v[136:137], v[240:241]
	global_store_dwordx4 v[226:227], v[148:151], off offset:16
	s_waitcnt vmcnt(6)
; __device__ __forceinline__ void unpack8(const u32x4 w, f32x4& a, f32x4& b) { a = (f32x4){bf_lo(w.x), bf_hi(w.x), bf_lo(w.y), bf_hi(w.y)}; b = (f32x4){bf_lo(w.z), bf_hi(w.z), bf_lo(w.w), bf_hi(w.w)}; }
;     __device__ __forceinline__ void operator()(AccRef acc, const Unit& u, int wr, int wc, int fr, int fq) const {
;     ...
;         f32x4 gv[2][2];
; #pragma unroll
;         for (int bj = 0; bj < 2; ++bj) { gv[bj][0] = *(const f32x4*)(g3 + colb + bj * 128); gv[bj][1] = *(const f32x4*)(g3 + colb + bj * 128 + 4); }
; #pragma unroll
;         for (int am = 0; am < 4; ++am) { const int ai = am >> 1, m0 = (am & 1) * 2; u32x4 xw[2][2]; float rs[2];
; #pragma unroll
;             for (int mm = 0; mm < 2; ++mm) { rs[mm] = __hip_atomic_load(ssq3 + rowb + ai * 128 + (m0 + mm) * 16, __ATOMIC_RELAXED, __HIP_MEMORY_SCOPE_AGENT);
; #pragma unroll
;                 for (int bj = 0; bj < 2; ++bj) xw[mm][bj] = *(const u32x4*)(X1B + (size_t)(rowb + ai * 128 + (m0 + mm) * 16) * D + colb + bj * 128); }
; #pragma unroll
;             for (int mm = 0; mm < 2; ++mm) { const int m = m0 + mm; const float r3 = rsqrtf(rs[mm] * (1.0f / D) + EPS); float* orow = out + (size_t)(rowb + ai * 128 + m * 16) * D + colb;
; #pragma unroll
;                 for (int bj = 0; bj < 2; ++bj) { f32x4 x0, x1; unpack8(xw[mm][bj], x0, x1);
;                     *(f32x4*)(orow + bj * 128) = (acc[ai][bj][m][0] + x0) * r3 * gv[bj][0]; *(f32x4*)(orow + bj * 128 + 4) = (acc[ai][bj][m][1] + x1) * r3 * gv[bj][1]; } }
;             asm volatile("" ::: "memory"); }
	s_nop 0
	v_lshlrev_b32_e32 v148, 16, v192
	v_and_b32_e32 v149, 0xffff0000, v192
	v_lshlrev_b32_e32 v150, 16, v193
	v_and_b32_e32 v151, 0xffff0000, v193
	v_pk_add_f32 v[150:151], v[94:95], v[150:151]
	v_pk_add_f32 v[148:149], v[92:93], v[148:149]
	v_pk_mul_f32 v[150:151], v[230:231], v[150:151] op_sel_hi:[0,1]
	v_pk_mul_f32 v[148:149], v[230:231], v[148:149] op_sel_hi:[0,1]
	v_lshlrev_b32_e32 v192, 16, v194
	v_and_b32_e32 v193, 0xffff0000, v194
	v_lshlrev_b32_e32 v194, 16, v195
	v_and_b32_e32 v195, 0xffff0000, v195
	v_pk_mul_f32 v[150:151], v[134:135], v[150:151]
	v_pk_mul_f32 v[148:149], v[132:133], v[148:149]
	global_store_dwordx4 v[226:227], v[148:151], off offset:512
	s_nop 1
	v_pk_add_f32 v[148:149], v[86:87], v[194:195]
	v_pk_add_f32 v[150:151], v[84:85], v[192:193]
	v_pk_mul_f32 v[148:149], v[230:231], v[148:149] op_sel_hi:[0,1]
	v_pk_mul_f32 v[192:193], v[230:231], v[150:151] op_sel_hi:[0,1]
	v_pk_mul_f32 v[150:151], v[130:131], v[148:149]
	v_pk_mul_f32 v[148:149], v[128:129], v[192:193]
	global_store_dwordx4 v[226:227], v[148:151], off offset:528
	global_load_dword v207, v[172:173], off offset:128 sc1
	global_load_dwordx4 v[148:151], v[188:189], off offset:-4096
	global_load_dwordx4 v[192:195], v[188:189], off
	global_load_dword v206, v[172:173], off offset:192 sc1
	global_load_dwordx4 v[202:205], v[184:185], off offset:-4096
	global_load_dwordx4 v[212:215], v[184:185], off
	s_waitcnt vmcnt(4)
	v_lshlrev_b32_e32 v184, 16, v148
	s_waitcnt vmcnt(3)
	v_lshlrev_b32_e32 v218, 16, v194
	s_waitcnt vmcnt(2)
	v_pk_fma_f32 v[206:207], v[206:207], s[38:39], v[146:147] op_sel_hi:[1,0,0]
	v_and_b32_e32 v219, 0xffff0000, v194
	v_mul_f32_e32 v220, 0x4b800000, v207
	v_cmp_gt_f32_e32 vcc, s83, v207
	v_mul_f32_e32 v221, 0x4b800000, v206
	v_cmp_gt_f32_e64 s[8:9], s83, v206
	v_cndmask_b32_e32 v207, v207, v220, vcc
	v_rsq_f32_e32 v220, v207
	v_cndmask_b32_e64 v206, v206, v221, s[8:9]
	v_rsq_f32_e32 v221, v206
	v_and_b32_e32 v185, 0xffff0000, v148
	v_lshlrev_b32_e32 v148, 16, v149
	v_and_b32_e32 v149, 0xffff0000, v149
	v_pk_add_f32 v[206:207], v[72:73], v[218:219]
	v_mul_f32_e32 v218, 0x45800000, v220
	v_lshlrev_b32_e32 v188, 16, v150
	v_and_b32_e32 v189, 0xffff0000, v150
	v_lshlrev_b32_e32 v150, 16, v151
	v_and_b32_e32 v151, 0xffff0000, v151
	v_lshlrev_b32_e32 v216, 16, v192
	v_and_b32_e32 v217, 0xffff0000, v192
	v_lshlrev_b32_e32 v192, 16, v193
	v_and_b32_e32 v193, 0xffff0000, v193
	v_lshlrev_b32_e32 v194, 16, v195
	v_and_b32_e32 v195, 0xffff0000, v195
	v_pk_add_f32 v[148:149], v[106:107], v[148:149]
	v_pk_add_f32 v[184:185], v[104:105], v[184:185]
	v_mul_f32_e32 v219, 0x45800000, v221
	v_cndmask_b32_e32 v218, v220, v218, vcc
	v_pk_add_f32 v[150:151], v[98:99], v[150:151]
	v_pk_add_f32 v[188:189], v[96:97], v[188:189]
	v_pk_add_f32 v[192:193], v[78:79], v[192:193]
	v_pk_add_f32 v[216:217], v[76:77], v[216:217]
	v_pk_add_f32 v[194:195], v[74:75], v[194:195]
	v_pk_mul_f32 v[184:185], v[184:185], v[218:219] op_sel_hi:[1,0]
	v_pk_mul_f32 v[148:149], v[148:149], v[218:219] op_sel_hi:[1,0]
	v_cndmask_b32_e64 v224, v221, v219, s[8:9]
	v_pk_mul_f32 v[188:189], v[188:189], v[218:219] op_sel_hi:[1,0]
	v_pk_mul_f32 v[220:221], v[150:151], v[218:219] op_sel_hi:[1,0]
	v_pk_mul_f32 v[216:217], v[218:219], v[216:217] op_sel_hi:[0,1]
	v_pk_mul_f32 v[222:223], v[218:219], v[192:193] op_sel_hi:[0,1]
	v_pk_mul_f32 v[206:207], v[218:219], v[206:207] op_sel_hi:[0,1]
	v_pk_mul_f32 v[226:227], v[218:219], v[194:195] op_sel_hi:[0,1]
	v_pk_mul_f32 v[150:151], v[142:143], v[148:149]
	v_pk_mul_f32 v[148:149], v[140:141], v[184:185]
	v_pk_mul_f32 v[194:195], v[138:139], v[220:221]
	v_pk_mul_f32 v[192:193], v[136:137], v[188:189]
	v_pk_mul_f32 v[218:219], v[134:135], v[222:223]
	v_pk_mul_f32 v[216:217], v[132:133], v[216:217]
	v_pk_mul_f32 v[222:223], v[130:131], v[226:227]
	v_pk_mul_f32 v[220:221], v[128:129], v[206:207]
	global_store_dwordx4 v[180:181], v[148:151], off
	global_store_dwordx4 v[180:181], v[192:195], off offset:16
	global_store_dwordx4 v[180:181], v[216:219], off offset:512
	global_store_dwordx4 v[180:181], v[220:223], off offset:528
	v_lshlrev_b64 v[148:149], 13, v[174:175]
	v_lshl_add_u64 v[148:149], s[28:29], 0, v[148:149]
	v_lshl_add_u64 v[174:175], v[148:149], 0, v[144:145]
	s_waitcnt vmcnt(5)
	v_lshlrev_b32_e32 v148, 16, v202
	v_and_b32_e32 v149, 0xffff0000, v202
	v_lshlrev_b32_e32 v150, 16, v203
	v_and_b32_e32 v151, 0xffff0000, v203
	v_pk_add_f32 v[150:151], v[90:91], v[150:151]
	v_pk_add_f32 v[148:149], v[88:89], v[148:149]
	v_pk_mul_f32 v[150:151], v[150:151], v[224:225] op_sel_hi:[1,0]
	v_pk_mul_f32 v[148:149], v[148:149], v[224:225] op_sel_hi:[1,0]
	v_lshlrev_b32_e32 v180, 16, v204
	v_and_b32_e32 v181, 0xffff0000, v204
	v_lshlrev_b32_e32 v184, 16, v205
	v_and_b32_e32 v185, 0xffff0000, v205
	v_pk_mul_f32 v[150:151], v[142:143], v[150:151]
	v_pk_mul_f32 v[148:149], v[140:141], v[148:149]
	global_store_dwordx4 v[174:175], v[148:151], off
	s_nop 1
	v_pk_add_f32 v[148:149], v[82:83], v[184:185]
	v_pk_add_f32 v[150:151], v[80:81], v[180:181]
	v_pk_mul_f32 v[148:149], v[148:149], v[224:225] op_sel_hi:[1,0]
	v_pk_mul_f32 v[180:181], v[150:151], v[224:225] op_sel_hi:[1,0]
	v_pk_mul_f32 v[150:151], v[138:139], v[148:149]
	v_pk_mul_f32 v[148:149], v[136:137], v[180:181]
	global_store_dwordx4 v[174:175], v[148:151], off offset:16
	s_waitcnt vmcnt(6)
; __device__ __forceinline__ void unpack8(const u32x4 w, f32x4& a, f32x4& b) { a = (f32x4){bf_lo(w.x), bf_hi(w.x), bf_lo(w.y), bf_hi(w.y)}; b = (f32x4){bf_lo(w.z), bf_hi(w.z), bf_lo(w.w), bf_hi(w.w)}; }
;     __device__ __forceinline__ void operator()(AccRef acc, const Unit& u, int wr, int wc, int fr, int fq) const {
;     ...
;         f32x4 gv[2][2];
; #pragma unroll
;         for (int bj = 0; bj < 2; ++bj) { gv[bj][0] = *(const f32x4*)(g3 + colb + bj * 128); gv[bj][1] = *(const f32x4*)(g3 + colb + bj * 128 + 4); }
; #pragma unroll
;         for (int am = 0; am < 4; ++am) { const int ai = am >> 1, m0 = (am & 1) * 2; u32x4 xw[2][2]; float rs[2];
; #pragma unroll
;             for (int mm = 0; mm < 2; ++mm) { rs[mm] = __hip_atomic_load(ssq3 + rowb + ai * 128 + (m0 + mm) * 16, __ATOMIC_RELAXED, __HIP_MEMORY_SCOPE_AGENT);
; #pragma unroll
;                 for (int bj = 0; bj < 2; ++bj) xw[mm][bj] = *(const u32x4*)(X1B + (size_t)(rowb + ai * 128 + (m0 + mm) * 16) * D + colb + bj * 128); }
; #pragma unroll
;             for (int mm = 0; mm < 2; ++mm) { const int m = m0 + mm; const float r3 = rsqrtf(rs[mm] * (1.0f / D) + EPS); float* orow = out + (size_t)(rowb + ai * 128 + m * 16) * D + colb;
; #pragma unroll
;                 for (int bj = 0; bj < 2; ++bj) { f32x4 x0, x1; unpack8(xw[mm][bj], x0, x1);
;                     *(f32x4*)(orow + bj * 128) = (acc[ai][bj][m][0] + x0) * r3 * gv[bj][0]; *(f32x4*)(orow + bj * 128 + 4) = (acc[ai][bj][m][1] + x1) * r3 * gv[bj][1]; } }
;             asm volatile("" ::: "memory"); }
	v_lshlrev_b32_e32 v180, 16, v214
	v_and_b32_e32 v181, 0xffff0000, v214
	v_lshlrev_b32_e32 v148, 16, v212
	v_and_b32_e32 v149, 0xffff0000, v212
	v_lshlrev_b32_e32 v150, 16, v213
	v_and_b32_e32 v151, 0xffff0000, v213
	v_pk_add_f32 v[150:151], v[70:71], v[150:151]
	v_pk_add_f32 v[148:149], v[68:69], v[148:149]
	v_pk_mul_f32 v[150:151], v[224:225], v[150:151] op_sel_hi:[0,1]
	v_pk_mul_f32 v[148:149], v[224:225], v[148:149] op_sel_hi:[0,1]
	v_lshlrev_b32_e32 v184, 16, v215
	v_and_b32_e32 v185, 0xffff0000, v215
	v_pk_mul_f32 v[150:151], v[134:135], v[150:151]
	v_pk_mul_f32 v[148:149], v[132:133], v[148:149]
	global_store_dwordx4 v[174:175], v[148:151], off offset:512
	s_nop 1
	v_pk_add_f32 v[148:149], v[66:67], v[184:185]
	v_pk_add_f32 v[150:151], v[64:65], v[180:181]
	v_pk_mul_f32 v[148:149], v[224:225], v[148:149] op_sel_hi:[0,1]
	v_pk_mul_f32 v[180:181], v[224:225], v[150:151] op_sel_hi:[0,1]
	v_pk_mul_f32 v[150:151], v[130:131], v[148:149]
	v_pk_mul_f32 v[148:149], v[128:129], v[180:181]
	global_store_dwordx4 v[174:175], v[148:151], off offset:528
	global_load_dword v175, v[172:173], off offset:512 sc1
	global_load_dwordx4 v[148:151], v[198:199], off offset:-4096
	global_load_dwordx4 v[192:195], v[198:199], off
	global_load_dword v174, v[172:173], off offset:576 sc1
	global_load_dwordx4 v[202:205], v[200:201], off offset:-4096
	v_lshlrev_b64 v[180:181], 13, v[196:197]
	global_load_dwordx4 v[196:199], v[200:201], off
	v_lshl_add_u64 v[180:181], s[28:29], 0, v[180:181]
	v_lshl_add_u64 v[180:181], v[180:181], 0, v[144:145]
	s_waitcnt vmcnt(4)
	v_lshlrev_b32_e32 v188, 16, v150
	v_and_b32_e32 v189, 0xffff0000, v150
	v_lshlrev_b32_e32 v150, 16, v151
	v_and_b32_e32 v151, 0xffff0000, v151
	s_waitcnt vmcnt(2)
	v_pk_fma_f32 v[174:175], v[174:175], s[38:39], v[146:147] op_sel_hi:[1,0,0]
	v_pk_add_f32 v[212:213], v[58:59], v[150:151]
	v_mul_f32_e32 v150, 0x4b800000, v175
	v_cmp_gt_f32_e32 vcc, s83, v175
	v_lshlrev_b32_e32 v184, 16, v148
	v_and_b32_e32 v185, 0xffff0000, v148
	v_cndmask_b32_e32 v150, v175, v150, vcc
	v_rsq_f32_e32 v150, v150
	v_lshlrev_b32_e32 v148, 16, v149
	v_and_b32_e32 v149, 0xffff0000, v149
	v_pk_add_f32 v[148:149], v[62:63], v[148:149]
	v_mul_f32_e32 v151, 0x45800000, v150
	v_pk_add_f32 v[184:185], v[60:61], v[184:185]
	v_cndmask_b32_e32 v214, v150, v151, vcc
	v_pk_mul_f32 v[184:185], v[184:185], v[214:215] op_sel_hi:[1,0]
	v_pk_mul_f32 v[148:149], v[148:149], v[214:215] op_sel_hi:[1,0]
	v_pk_add_f32 v[188:189], v[56:57], v[188:189]
	v_pk_mul_f32 v[150:151], v[142:143], v[148:149]
	v_pk_mul_f32 v[148:149], v[140:141], v[184:185]
	v_lshlrev_b32_e32 v200, 16, v192
	v_and_b32_e32 v201, 0xffff0000, v192
	v_lshlrev_b32_e32 v192, 16, v193
	v_and_b32_e32 v193, 0xffff0000, v193
	global_store_dwordx4 v[180:181], v[148:151], off
	v_mul_f32_e32 v175, 0x4b800000, v174
	v_cmp_gt_f32_e32 vcc, s83, v174
	v_pk_mul_f32 v[148:149], v[188:189], v[214:215] op_sel_hi:[1,0]
	v_pk_mul_f32 v[150:151], v[212:213], v[214:215] op_sel_hi:[1,0]
	v_pk_add_f32 v[192:193], v[46:47], v[192:193]
	v_pk_add_f32 v[200:201], v[44:45], v[200:201]
	v_pk_mul_f32 v[150:151], v[138:139], v[150:151]
	v_pk_mul_f32 v[148:149], v[136:137], v[148:149]
	v_cndmask_b32_e32 v174, v174, v175, vcc
	v_lshlrev_b32_e32 v206, 16, v194
	v_and_b32_e32 v207, 0xffff0000, v194
	v_lshlrev_b32_e32 v194, 16, v195
	v_and_b32_e32 v195, 0xffff0000, v195
	global_store_dwordx4 v[180:181], v[148:151], off offset:16
	v_rsq_f32_e32 v174, v174
	v_pk_add_f32 v[194:195], v[38:39], v[194:195]
	v_pk_mul_f32 v[148:149], v[214:215], v[200:201] op_sel_hi:[0,1]
	v_pk_mul_f32 v[150:151], v[214:215], v[192:193] op_sel_hi:[0,1]
	v_pk_add_f32 v[206:207], v[36:37], v[206:207]
	v_pk_mul_f32 v[150:151], v[134:135], v[150:151]
	v_pk_mul_f32 v[148:149], v[132:133], v[148:149]
	global_store_dwordx4 v[180:181], v[148:151], off offset:512
	s_waitcnt vmcnt(4)
	v_lshlrev_b32_e32 v184, 16, v204
	v_and_b32_e32 v185, 0xffff0000, v204
	v_pk_mul_f32 v[148:149], v[214:215], v[206:207] op_sel_hi:[0,1]
	v_pk_mul_f32 v[150:151], v[214:215], v[194:195] op_sel_hi:[0,1]
	v_pk_mul_f32 v[150:151], v[130:131], v[150:151]
	v_pk_mul_f32 v[148:149], v[128:129], v[148:149]
	global_store_dwordx4 v[180:181], v[148:151], off offset:528
	v_lshlrev_b32_e32 v188, 16, v205
	v_and_b32_e32 v189, 0xffff0000, v205
	v_mul_f32_e32 v148, 0x45800000, v174
	v_cndmask_b32_e32 v174, v174, v148, vcc
	v_lshlrev_b64 v[148:149], 13, v[190:191]
	v_lshl_add_u64 v[148:149], s[28:29], 0, v[148:149]
	v_lshl_add_u64 v[180:181], v[148:149], 0, v[144:145]
	v_lshlrev_b32_e32 v148, 16, v202
	v_and_b32_e32 v149, 0xffff0000, v202
	v_lshlrev_b32_e32 v150, 16, v203
	v_and_b32_e32 v151, 0xffff0000, v203
	v_pk_add_f32 v[150:151], v[54:55], v[150:151]
	v_pk_add_f32 v[148:149], v[52:53], v[148:149]
	v_pk_mul_f32 v[150:151], v[150:151], v[174:175] op_sel_hi:[1,0]
	v_pk_mul_f32 v[148:149], v[148:149], v[174:175] op_sel_hi:[1,0]
	v_pk_mul_f32 v[150:151], v[142:143], v[150:151]
	v_pk_mul_f32 v[148:149], v[140:141], v[148:149]
	global_store_dwordx4 v[180:181], v[148:151], off
	v_lshl_add_u64 v[190:191], v[178:179], 0, v[144:145]
	s_nop 0
	v_pk_add_f32 v[148:149], v[50:51], v[188:189]
	v_pk_add_f32 v[150:151], v[48:49], v[184:185]
	v_pk_mul_f32 v[148:149], v[148:149], v[174:175] op_sel_hi:[1,0]
	v_pk_mul_f32 v[184:185], v[150:151], v[174:175] op_sel_hi:[1,0]
	v_pk_mul_f32 v[150:151], v[138:139], v[148:149]
	v_pk_mul_f32 v[148:149], v[136:137], v[184:185]
	global_store_dwordx4 v[180:181], v[148:151], off offset:16
	s_waitcnt vmcnt(6)
; __device__ __forceinline__ void unpack8(const u32x4 w, f32x4& a, f32x4& b) { a = (f32x4){bf_lo(w.x), bf_hi(w.x), bf_lo(w.y), bf_hi(w.y)}; b = (f32x4){bf_lo(w.z), bf_hi(w.z), bf_lo(w.w), bf_hi(w.w)}; }
;     __device__ __forceinline__ void operator()(AccRef acc, const Unit& u, int wr, int wc, int fr, int fq) const {
;     ...
;         f32x4 gv[2][2];
; #pragma unroll
;         for (int bj = 0; bj < 2; ++bj) { gv[bj][0] = *(const f32x4*)(g3 + colb + bj * 128); gv[bj][1] = *(const f32x4*)(g3 + colb + bj * 128 + 4); }
; #pragma unroll
;         for (int am = 0; am < 4; ++am) { const int ai = am >> 1, m0 = (am & 1) * 2; u32x4 xw[2][2]; float rs[2];
; #pragma unroll
;             for (int mm = 0; mm < 2; ++mm) { rs[mm] = __hip_atomic_load(ssq3 + rowb + ai * 128 + (m0 + mm) * 16, __ATOMIC_RELAXED, __HIP_MEMORY_SCOPE_AGENT);
; #pragma unroll
;                 for (int bj = 0; bj < 2; ++bj) xw[mm][bj] = *(const u32x4*)(X1B + (size_t)(rowb + ai * 128 + (m0 + mm) * 16) * D + colb + bj * 128); }
; #pragma unroll
;             for (int mm = 0; mm < 2; ++mm) { const int m = m0 + mm; const float r3 = rsqrtf(rs[mm] * (1.0f / D) + EPS); float* orow = out + (size_t)(rowb + ai * 128 + m * 16) * D + colb;
; #pragma unroll
;                 for (int bj = 0; bj < 2; ++bj) { f32x4 x0, x1; unpack8(xw[mm][bj], x0, x1);
;                     *(f32x4*)(orow + bj * 128) = (acc[ai][bj][m][0] + x0) * r3 * gv[bj][0]; *(f32x4*)(orow + bj * 128 + 4) = (acc[ai][bj][m][1] + x1) * r3 * gv[bj][1]; } }
;             asm volatile("" ::: "memory"); }
	v_lshlrev_b32_e32 v184, 16, v198
	v_and_b32_e32 v185, 0xffff0000, v198
	v_lshlrev_b32_e32 v148, 16, v196
	v_and_b32_e32 v149, 0xffff0000, v196
	v_lshlrev_b32_e32 v150, 16, v197
	v_and_b32_e32 v151, 0xffff0000, v197
	v_pk_add_f32 v[150:151], v[30:31], v[150:151]
	v_pk_add_f32 v[148:149], v[28:29], v[148:149]
	v_pk_mul_f32 v[150:151], v[174:175], v[150:151] op_sel_hi:[0,1]
	v_pk_mul_f32 v[148:149], v[174:175], v[148:149] op_sel_hi:[0,1]
	v_lshlrev_b32_e32 v188, 16, v199
	v_and_b32_e32 v189, 0xffff0000, v199
	v_pk_mul_f32 v[150:151], v[134:135], v[150:151]
	v_pk_mul_f32 v[148:149], v[132:133], v[148:149]
	global_store_dwordx4 v[180:181], v[148:151], off offset:512
	s_nop 1
	v_pk_add_f32 v[148:149], v[22:23], v[188:189]
	v_pk_add_f32 v[150:151], v[20:21], v[184:185]
	v_pk_mul_f32 v[148:149], v[174:175], v[148:149] op_sel_hi:[0,1]
	v_pk_mul_f32 v[184:185], v[174:175], v[150:151] op_sel_hi:[0,1]
	v_pk_mul_f32 v[150:151], v[130:131], v[148:149]
	v_pk_mul_f32 v[148:149], v[128:129], v[184:185]
	global_store_dwordx4 v[180:181], v[148:151], off offset:528
	global_load_dword v189, v[172:173], off offset:640 sc1
	global_load_dwordx4 v[148:151], v[186:187], off offset:-4096
	s_nop 0
	global_load_dwordx4 v[184:187], v[186:187], off
	s_nop 0
	global_load_dword v188, v[172:173], off offset:704 sc1
	s_nop 0
	global_load_dwordx4 v[172:175], v[182:183], off offset:-4096
	global_load_dwordx4 v[178:181], v[182:183], off
	s_waitcnt vmcnt(4)
	v_lshlrev_b32_e32 v182, 16, v148
	v_and_b32_e32 v183, 0xffff0000, v148
	s_waitcnt vmcnt(2)
	v_pk_fma_f32 v[188:189], v[188:189], s[38:39], v[146:147] op_sel_hi:[1,0,0]
	v_lshlrev_b32_e32 v148, 16, v149
	v_mul_f32_e32 v146, 0x4b800000, v189
	v_cmp_gt_f32_e32 vcc, s83, v189
	v_and_b32_e32 v149, 0xffff0000, v149
	v_pk_add_f32 v[148:149], v[42:43], v[148:149]
	v_cndmask_b32_e32 v146, v189, v146, vcc
	v_rsq_f32_e32 v146, v146
	v_pk_add_f32 v[182:183], v[40:41], v[182:183]
	v_lshlrev_b32_e32 v192, 16, v150
	v_and_b32_e32 v193, 0xffff0000, v150
	v_mul_f32_e32 v147, 0x45800000, v146
	v_cndmask_b32_e32 v198, v146, v147, vcc
	v_lshlrev_b32_e32 v150, 16, v151
	v_and_b32_e32 v151, 0xffff0000, v151
	v_pk_mul_f32 v[146:147], v[182:183], v[198:199] op_sel_hi:[1,0]
	v_pk_mul_f32 v[148:149], v[148:149], v[198:199] op_sel_hi:[1,0]
	v_pk_add_f32 v[150:151], v[34:35], v[150:151]
	v_pk_add_f32 v[192:193], v[32:33], v[192:193]
	v_pk_mul_f32 v[148:149], v[142:143], v[148:149]
	v_pk_mul_f32 v[146:147], v[140:141], v[146:147]
	v_lshlrev_b32_e32 v194, 16, v184
	v_and_b32_e32 v195, 0xffff0000, v184
	v_lshlrev_b32_e32 v184, 16, v185
	v_and_b32_e32 v185, 0xffff0000, v185
	global_store_dwordx4 v[190:191], v[146:149], off
	v_pk_add_f32 v[184:185], v[14:15], v[184:185]
	v_pk_add_f32 v[194:195], v[12:13], v[194:195]
	v_pk_mul_f32 v[146:147], v[192:193], v[198:199] op_sel_hi:[1,0]
	v_pk_mul_f32 v[148:149], v[150:151], v[198:199] op_sel_hi:[1,0]
	v_pk_mul_f32 v[146:147], v[136:137], v[146:147]
	v_pk_mul_f32 v[148:149], v[138:139], v[148:149]
	v_mul_f32_e32 v150, 0x4b800000, v188
	v_cmp_gt_f32_e32 vcc, s83, v188
	v_lshlrev_b32_e32 v196, 16, v186
	v_and_b32_e32 v197, 0xffff0000, v186
	v_lshlrev_b32_e32 v186, 16, v187
	v_and_b32_e32 v187, 0xffff0000, v187
	global_store_dwordx4 v[190:191], v[146:149], off offset:16
	v_cndmask_b32_e32 v150, v188, v150, vcc
	v_pk_add_f32 v[186:187], v[10:11], v[186:187]
	v_pk_mul_f32 v[146:147], v[198:199], v[194:195] op_sel_hi:[0,1]
	v_pk_mul_f32 v[148:149], v[198:199], v[184:185] op_sel_hi:[0,1]
	v_pk_add_f32 v[196:197], v[8:9], v[196:197]
	v_pk_mul_f32 v[148:149], v[134:135], v[148:149]
	v_pk_mul_f32 v[146:147], v[132:133], v[146:147]
	v_rsq_f32_e32 v150, v150
	global_store_dwordx4 v[190:191], v[146:149], off offset:512
	s_waitcnt vmcnt(4)
	v_and_b32_e32 v151, 0xffff0000, v173
	v_pk_mul_f32 v[146:147], v[198:199], v[196:197] op_sel_hi:[0,1]
	v_pk_mul_f32 v[148:149], v[198:199], v[186:187] op_sel_hi:[0,1]
	v_pk_mul_f32 v[148:149], v[130:131], v[148:149]
	v_pk_mul_f32 v[146:147], v[128:129], v[146:147]
	global_store_dwordx4 v[190:191], v[146:149], off offset:528
	s_nop 1
	v_lshlrev_b64 v[148:149], 13, v[176:177]
	v_mul_f32_e32 v146, 0x45800000, v150
	v_lshl_add_u64 v[148:149], s[28:29], 0, v[148:149]
	v_cndmask_b32_e32 v146, v150, v146, vcc
	v_lshl_add_u64 v[144:145], v[148:149], 0, v[144:145]
	v_lshlrev_b32_e32 v148, 16, v172
	v_and_b32_e32 v149, 0xffff0000, v172
	v_lshlrev_b32_e32 v150, 16, v173
	v_pk_add_f32 v[150:151], v[26:27], v[150:151]
	v_pk_add_f32 v[148:149], v[24:25], v[148:149]
	v_pk_mul_f32 v[150:151], v[150:151], v[146:147] op_sel_hi:[1,0]
	v_pk_mul_f32 v[148:149], v[148:149], v[146:147] op_sel_hi:[1,0]
	v_lshlrev_b32_e32 v172, 16, v174
	v_and_b32_e32 v173, 0xffff0000, v174
	v_lshlrev_b32_e32 v174, 16, v175
	v_and_b32_e32 v175, 0xffff0000, v175
	v_pk_mul_f32 v[142:143], v[142:143], v[150:151]
	v_pk_mul_f32 v[140:141], v[140:141], v[148:149]
	global_store_dwordx4 v[144:145], v[140:143], off
	s_nop 1
	v_pk_add_f32 v[140:141], v[18:19], v[174:175]
	v_pk_add_f32 v[142:143], v[16:17], v[172:173]
	v_pk_mul_f32 v[140:141], v[140:141], v[146:147] op_sel_hi:[1,0]
	v_pk_mul_f32 v[142:143], v[142:143], v[146:147] op_sel_hi:[1,0]
	v_pk_mul_f32 v[138:139], v[138:139], v[140:141]
	v_pk_mul_f32 v[136:137], v[136:137], v[142:143]
	global_store_dwordx4 v[144:145], v[136:139], off offset:16
	s_waitcnt vmcnt(6)
	v_lshlrev_b32_e32 v140, 16, v180
	v_and_b32_e32 v141, 0xffff0000, v180
	v_lshlrev_b32_e32 v136, 16, v178
	v_and_b32_e32 v137, 0xffff0000, v178
	v_lshlrev_b32_e32 v138, 16, v179
	v_and_b32_e32 v139, 0xffff0000, v179
	v_pk_add_f32 v[138:139], v[6:7], v[138:139]
	v_pk_add_f32 v[136:137], v[4:5], v[136:137]
	v_pk_mul_f32 v[138:139], v[146:147], v[138:139] op_sel_hi:[0,1]
	v_pk_mul_f32 v[136:137], v[146:147], v[136:137] op_sel_hi:[0,1]
	v_lshlrev_b32_e32 v142, 16, v181
	v_and_b32_e32 v143, 0xffff0000, v181
	v_pk_mul_f32 v[134:135], v[134:135], v[138:139]
	v_pk_mul_f32 v[132:133], v[132:133], v[136:137]
	global_store_dwordx4 v[144:145], v[132:135], off offset:512
	s_nop 1
	v_pk_add_f32 v[132:133], v[2:3], v[142:143]
	v_pk_add_f32 v[134:135], v[0:1], v[140:141]
	v_pk_mul_f32 v[132:133], v[146:147], v[132:133] op_sel_hi:[0,1]
	v_pk_mul_f32 v[134:135], v[146:147], v[134:135] op_sel_hi:[0,1]
	v_pk_mul_f32 v[130:131], v[130:131], v[132:133]
	v_pk_mul_f32 v[128:129], v[128:129], v[134:135]
	global_store_dwordx4 v[144:145], v[128:131], off offset:528
